# GEMM compute segments (P1/P3/P4/P5a): deleted the mid-run s_setprio 0/1 pair and the duplicate lgkmcnt(0) behind the barrier (3 issue slots per 32-MFMA super-phase)
# speedup vs baseline: 1.0146x; 1.0049x over previous
.LBB0_101:
	ds_read_b128 v[128:131], v170
	ds_read_b128 v[132:135], v170 offset:1024
	ds_read_b128 v[162:165], v170 offset:2048
	ds_read_b128 v[166:169], v170 offset:3072
	ds_read_b128 v[174:177], v171
	ds_read_b128 v[178:181], v171 offset:1024
	ds_read_b128 v[182:185], v171 offset:2048
	ds_read_b128 v[186:189], v171 offset:3072
	s_add_u32 s6, s4, 0xfffc0080
	s_addc_u32 s7, s5, -1
	s_cmp_eq_u32 s21, 12
	s_cselect_b32 s19, s0, s7
	s_cselect_b32 s18, s1, s6
	s_cselect_b32 s7, s3, s20
	s_cselect_b32 s6, s14, s17
	v_lshl_add_u64 v[222:223], s[4:5], 0, v[154:155]
	s_add_i32 m0, s50, 0xc000
	ds_read_b128 v[190:193], v172
	ds_read_b128 v[194:197], v172 offset:1024
	ds_read_b128 v[198:201], v172 offset:2048
	ds_read_b128 v[202:205], v172 offset:3072
	ds_read_b128 v[206:209], v172 offset:4096
	ds_read_b128 v[210:213], v172 offset:5120
	ds_read_b128 v[214:217], v172 offset:6144
	ds_read_b128 v[218:221], v172 offset:7168
	global_load_lds_dwordx4 v[222:223], off
	v_lshl_add_u64 v[222:223], s[4:5], 0, v[156:157]
	s_add_i32 m0, s50, 0xe000
	s_nop 0
	global_load_lds_dwordx4 v[222:223], off
	s_waitcnt vmcnt(8)
	s_waitcnt lgkmcnt(0)
	s_barrier
	s_setprio 1
	v_mfma_f32_16x16x32_bf16 v[124:127], v[128:131], v[190:193], v[124:127]
	v_mfma_f32_16x16x32_bf16 v[120:123], v[162:165], v[190:193], v[120:123]
	v_mfma_f32_16x16x32_bf16 v[108:111], v[128:131], v[198:201], v[108:111]
	v_mfma_f32_16x16x32_bf16 v[104:107], v[162:165], v[198:201], v[104:107]
	v_mfma_f32_16x16x32_bf16 v[92:95], v[128:131], v[206:209], v[92:95]
	v_mfma_f32_16x16x32_bf16 v[88:91], v[162:165], v[206:209], v[88:91]
	v_mfma_f32_16x16x32_bf16 v[76:79], v[128:131], v[214:217], v[76:79]
	v_mfma_f32_16x16x32_bf16 v[72:75], v[162:165], v[214:217], v[72:75]
	v_mfma_f32_16x16x32_bf16 v[124:127], v[132:135], v[194:197], v[124:127]
	v_mfma_f32_16x16x32_bf16 v[120:123], v[166:169], v[194:197], v[120:123]
	v_mfma_f32_16x16x32_bf16 v[108:111], v[132:135], v[202:205], v[108:111]
	v_mfma_f32_16x16x32_bf16 v[104:107], v[166:169], v[202:205], v[104:107]
	v_mfma_f32_16x16x32_bf16 v[92:95], v[132:135], v[210:213], v[92:95]
	v_mfma_f32_16x16x32_bf16 v[88:91], v[166:169], v[210:213], v[88:91]
	v_mfma_f32_16x16x32_bf16 v[76:79], v[132:135], v[218:221], v[76:79]
	v_mfma_f32_16x16x32_bf16 v[72:75], v[166:169], v[218:221], v[72:75]
	v_mfma_f32_16x16x32_bf16 v[116:119], v[174:177], v[190:193], v[116:119]
	v_mfma_f32_16x16x32_bf16 v[112:115], v[182:185], v[190:193], v[112:115]
	v_mfma_f32_16x16x32_bf16 v[100:103], v[174:177], v[198:201], v[100:103]
	v_mfma_f32_16x16x32_bf16 v[96:99], v[182:185], v[198:201], v[96:99]
	v_mfma_f32_16x16x32_bf16 v[84:87], v[174:177], v[206:209], v[84:87]
	v_mfma_f32_16x16x32_bf16 v[80:83], v[182:185], v[206:209], v[80:83]
	v_mfma_f32_16x16x32_bf16 v[68:71], v[174:177], v[214:217], v[68:71]
	v_mfma_f32_16x16x32_bf16 v[64:67], v[182:185], v[214:217], v[64:67]
	v_mfma_f32_16x16x32_bf16 v[116:119], v[178:181], v[194:197], v[116:119]
	v_mfma_f32_16x16x32_bf16 v[112:115], v[186:189], v[194:197], v[112:115]
	v_mfma_f32_16x16x32_bf16 v[100:103], v[178:181], v[202:205], v[100:103]
	v_mfma_f32_16x16x32_bf16 v[96:99], v[186:189], v[202:205], v[96:99]
	v_mfma_f32_16x16x32_bf16 v[84:87], v[178:181], v[210:213], v[84:87]
	v_mfma_f32_16x16x32_bf16 v[80:83], v[186:189], v[210:213], v[80:83]
	v_mfma_f32_16x16x32_bf16 v[68:71], v[178:181], v[218:221], v[68:71]
	v_mfma_f32_16x16x32_bf16 v[64:67], v[186:189], v[218:221], v[64:67]
	s_setprio 0
	s_barrier
	s_add_i32 s24, s95, s23
	v_lshl_add_u64 v[222:223], s[6:7], 0, v[138:139]
	s_mov_b32 m0, s24
	ds_read_b128 v[190:193], v172 offset:16384
	ds_read_b128 v[194:197], v172 offset:17408
	ds_read_b128 v[198:201], v172 offset:18432
	ds_read_b128 v[202:205], v172 offset:19456
	ds_read_b128 v[206:209], v172 offset:20480
	ds_read_b128 v[210:213], v172 offset:21504
	ds_read_b128 v[214:217], v172 offset:22528
	ds_read_b128 v[218:221], v172 offset:23552
	global_load_lds_dwordx4 v[222:223], off
	s_add_i32 m0, s24, 0x2000
	s_add_u32 s28, s6, 0x40000
	v_lshl_add_u64 v[224:225], s[6:7], 0, v[142:143]
	s_addc_u32 s29, s7, 0
	s_add_i32 s24, s96, s23
	global_load_lds_dwordx4 v[224:225], off
	v_lshl_add_u64 v[226:227], s[28:29], 0, v[138:139]
	s_mov_b32 m0, s24
	v_lshl_add_u64 v[228:229], s[18:19], 0, v[140:141]
	global_load_lds_dwordx4 v[226:227], off
	v_lshl_add_u64 v[226:227], s[28:29], 0, v[142:143]
	s_add_i32 m0, s24, 0x2000
	s_nop 0
	global_load_lds_dwordx4 v[226:227], off
	v_lshl_add_u64 v[226:227], s[18:19], 0, v[136:137]
	s_mov_b32 m0, s50
	s_nop 0
	global_load_lds_dwordx4 v[226:227], off
	s_mov_b32 m0, s51
	s_nop 0
	global_load_lds_dwordx4 v[228:229], off
	s_waitcnt vmcnt(8)
	s_waitcnt lgkmcnt(0)
	s_barrier
	s_setprio 1
	v_mfma_f32_16x16x32_bf16 v[60:63], v[128:131], v[190:193], v[60:63]
	v_mfma_f32_16x16x32_bf16 v[56:59], v[162:165], v[190:193], v[56:59]
	v_mfma_f32_16x16x32_bf16 v[44:47], v[128:131], v[198:201], v[44:47]
	v_mfma_f32_16x16x32_bf16 v[40:43], v[162:165], v[198:201], v[40:43]
	v_mfma_f32_16x16x32_bf16 v[28:31], v[128:131], v[206:209], v[28:31]
	v_mfma_f32_16x16x32_bf16 v[24:27], v[162:165], v[206:209], v[24:27]
	v_mfma_f32_16x16x32_bf16 v[12:15], v[128:131], v[214:217], v[12:15]
	v_mfma_f32_16x16x32_bf16 v[8:11], v[162:165], v[214:217], v[8:11]
	v_mfma_f32_16x16x32_bf16 v[60:63], v[132:135], v[194:197], v[60:63]
	v_mfma_f32_16x16x32_bf16 v[56:59], v[166:169], v[194:197], v[56:59]
	v_mfma_f32_16x16x32_bf16 v[44:47], v[132:135], v[202:205], v[44:47]
	v_mfma_f32_16x16x32_bf16 v[40:43], v[166:169], v[202:205], v[40:43]
	v_mfma_f32_16x16x32_bf16 v[28:31], v[132:135], v[210:213], v[28:31]
	v_mfma_f32_16x16x32_bf16 v[24:27], v[166:169], v[210:213], v[24:27]
	v_mfma_f32_16x16x32_bf16 v[12:15], v[132:135], v[218:221], v[12:15]
	v_mfma_f32_16x16x32_bf16 v[8:11], v[166:169], v[218:221], v[8:11]
	v_mfma_f32_16x16x32_bf16 v[52:55], v[174:177], v[190:193], v[52:55]
	v_mfma_f32_16x16x32_bf16 v[48:51], v[182:185], v[190:193], v[48:51]
	v_mfma_f32_16x16x32_bf16 v[36:39], v[174:177], v[198:201], v[36:39]
	v_mfma_f32_16x16x32_bf16 v[32:35], v[182:185], v[198:201], v[32:35]
	v_mfma_f32_16x16x32_bf16 v[20:23], v[174:177], v[206:209], v[20:23]
	v_mfma_f32_16x16x32_bf16 v[16:19], v[182:185], v[206:209], v[16:19]
	v_mfma_f32_16x16x32_bf16 v[4:7], v[174:177], v[214:217], v[4:7]
	v_mfma_f32_16x16x32_bf16 v[0:3], v[182:185], v[214:217], v[0:3]
	v_mfma_f32_16x16x32_bf16 v[52:55], v[178:181], v[194:197], v[52:55]
	v_mfma_f32_16x16x32_bf16 v[48:51], v[186:189], v[194:197], v[48:51]
	v_mfma_f32_16x16x32_bf16 v[36:39], v[178:181], v[202:205], v[36:39]
	v_mfma_f32_16x16x32_bf16 v[32:35], v[186:189], v[202:205], v[32:35]
	v_mfma_f32_16x16x32_bf16 v[20:23], v[178:181], v[210:213], v[20:23]
	v_mfma_f32_16x16x32_bf16 v[16:19], v[186:189], v[210:213], v[16:19]
	v_mfma_f32_16x16x32_bf16 v[4:7], v[178:181], v[218:221], v[4:7]
	v_mfma_f32_16x16x32_bf16 v[0:3], v[186:189], v[218:221], v[0:3]
	s_setprio 0
	s_barrier
	s_add_i32 s24, 0, 0x18000
	v_add_u32_e32 v144, s24, v149
	s_add_i32 s26, 0, 0x1c000
	ds_read_b128 v[128:131], v144
	ds_read_b128 v[132:135], v144 offset:1024
	ds_read_b128 v[162:165], v144 offset:2048
	ds_read_b128 v[166:169], v144 offset:3072
	v_add_u32_e32 v144, s26, v149
	ds_read_b128 v[174:177], v144
	ds_read_b128 v[178:181], v144 offset:1024
	ds_read_b128 v[182:185], v144 offset:2048
	ds_read_b128 v[186:189], v144 offset:3072
	s_add_u32 s18, s18, 0x40000
	s_addc_u32 s19, s19, 0
	s_mov_b32 m0, s71
	v_lshl_add_u64 v[230:231], s[18:19], 0, v[136:137]
	ds_read_b128 v[190:193], v172 offset:32768
	ds_read_b128 v[194:197], v172 offset:33792
	ds_read_b128 v[198:201], v172 offset:34816
	ds_read_b128 v[202:205], v172 offset:35840
	ds_read_b128 v[206:209], v172 offset:36864
	ds_read_b128 v[210:213], v172 offset:37888
	ds_read_b128 v[214:217], v172 offset:38912
	ds_read_b128 v[218:221], v172 offset:39936
	global_load_lds_dwordx4 v[230:231], off
	v_lshl_add_u64 v[230:231], s[18:19], 0, v[140:141]
	s_mov_b32 m0, s80
	s_nop 0
	global_load_lds_dwordx4 v[230:231], off
	s_waitcnt vmcnt(8)
	s_waitcnt lgkmcnt(0)
	s_barrier
	s_setprio 1
	v_mfma_f32_16x16x32_bf16 v[124:127], v[128:131], v[190:193], v[124:127]
	v_mfma_f32_16x16x32_bf16 v[120:123], v[162:165], v[190:193], v[120:123]
	v_mfma_f32_16x16x32_bf16 v[108:111], v[128:131], v[198:201], v[108:111]
	v_mfma_f32_16x16x32_bf16 v[104:107], v[162:165], v[198:201], v[104:107]
	v_mfma_f32_16x16x32_bf16 v[92:95], v[128:131], v[206:209], v[92:95]
	v_mfma_f32_16x16x32_bf16 v[88:91], v[162:165], v[206:209], v[88:91]
	v_mfma_f32_16x16x32_bf16 v[76:79], v[128:131], v[214:217], v[76:79]
	v_mfma_f32_16x16x32_bf16 v[72:75], v[162:165], v[214:217], v[72:75]
	v_mfma_f32_16x16x32_bf16 v[124:127], v[132:135], v[194:197], v[124:127]
	v_mfma_f32_16x16x32_bf16 v[120:123], v[166:169], v[194:197], v[120:123]
	v_mfma_f32_16x16x32_bf16 v[108:111], v[132:135], v[202:205], v[108:111]
	v_mfma_f32_16x16x32_bf16 v[104:107], v[166:169], v[202:205], v[104:107]
	v_mfma_f32_16x16x32_bf16 v[92:95], v[132:135], v[210:213], v[92:95]
	v_mfma_f32_16x16x32_bf16 v[88:91], v[166:169], v[210:213], v[88:91]
	v_mfma_f32_16x16x32_bf16 v[76:79], v[132:135], v[218:221], v[76:79]
	v_mfma_f32_16x16x32_bf16 v[72:75], v[166:169], v[218:221], v[72:75]
	v_mfma_f32_16x16x32_bf16 v[116:119], v[174:177], v[190:193], v[116:119]
	v_mfma_f32_16x16x32_bf16 v[112:115], v[182:185], v[190:193], v[112:115]
	v_mfma_f32_16x16x32_bf16 v[100:103], v[174:177], v[198:201], v[100:103]
	v_mfma_f32_16x16x32_bf16 v[96:99], v[182:185], v[198:201], v[96:99]
	v_mfma_f32_16x16x32_bf16 v[84:87], v[174:177], v[206:209], v[84:87]
	v_mfma_f32_16x16x32_bf16 v[80:83], v[182:185], v[206:209], v[80:83]
	v_mfma_f32_16x16x32_bf16 v[68:71], v[174:177], v[214:217], v[68:71]
	v_mfma_f32_16x16x32_bf16 v[64:67], v[182:185], v[214:217], v[64:67]
	v_mfma_f32_16x16x32_bf16 v[116:119], v[178:181], v[194:197], v[116:119]
	v_mfma_f32_16x16x32_bf16 v[112:115], v[186:189], v[194:197], v[112:115]
	v_mfma_f32_16x16x32_bf16 v[100:103], v[178:181], v[202:205], v[100:103]
	v_mfma_f32_16x16x32_bf16 v[96:99], v[186:189], v[202:205], v[96:99]
	v_mfma_f32_16x16x32_bf16 v[84:87], v[178:181], v[210:213], v[84:87]
	v_mfma_f32_16x16x32_bf16 v[80:83], v[186:189], v[210:213], v[80:83]
	v_mfma_f32_16x16x32_bf16 v[68:71], v[178:181], v[218:221], v[68:71]
	v_mfma_f32_16x16x32_bf16 v[64:67], v[186:189], v[218:221], v[64:67]
	s_setprio 0
	s_barrier
	s_add_i32 s18, s24, s23
	v_lshl_add_u64 v[222:223], v[222:223], 0, s[30:31]
	s_mov_b32 m0, s18
	ds_read_b128 v[190:193], v172 offset:49152
	ds_read_b128 v[194:197], v172 offset:50176
	ds_read_b128 v[198:201], v172 offset:51200
	ds_read_b128 v[202:205], v172 offset:52224
	ds_read_b128 v[206:209], v172 offset:53248
	ds_read_b128 v[210:213], v172 offset:54272
	ds_read_b128 v[214:217], v172 offset:55296
	ds_read_b128 v[218:221], v172 offset:56320
	global_load_lds_dwordx4 v[222:223], off
	s_add_i32 m0, s18, 0x2000
	s_add_u32 s6, s6, 0x40080
	v_lshl_add_u64 v[222:223], v[224:225], 0, s[30:31]
	s_addc_u32 s7, s7, 0
	s_add_i32 s18, s26, s23
	global_load_lds_dwordx4 v[222:223], off
	v_lshl_add_u64 v[222:223], s[6:7], 0, v[138:139]
	s_mov_b32 m0, s18
	s_nop 0
	global_load_lds_dwordx4 v[222:223], off
	v_lshl_add_u64 v[222:223], s[6:7], 0, v[142:143]
	s_add_i32 m0, s18, 0x2000
	s_nop 0
	global_load_lds_dwordx4 v[222:223], off
	v_lshl_add_u64 v[222:223], v[226:227], 0, s[30:31]
	s_mov_b32 m0, s91
	s_nop 0
	global_load_lds_dwordx4 v[222:223], off
	v_lshl_add_u64 v[222:223], v[228:229], 0, s[30:31]
	s_mov_b32 m0, s92
	s_nop 0
	global_load_lds_dwordx4 v[222:223], off
	s_waitcnt vmcnt(8)
	s_waitcnt lgkmcnt(0)
	s_barrier
	s_setprio 1
	v_mfma_f32_16x16x32_bf16 v[60:63], v[128:131], v[190:193], v[60:63]
	v_mfma_f32_16x16x32_bf16 v[56:59], v[162:165], v[190:193], v[56:59]
	v_mfma_f32_16x16x32_bf16 v[44:47], v[128:131], v[198:201], v[44:47]
	v_mfma_f32_16x16x32_bf16 v[40:43], v[162:165], v[198:201], v[40:43]
	v_mfma_f32_16x16x32_bf16 v[28:31], v[128:131], v[206:209], v[28:31]
	v_mfma_f32_16x16x32_bf16 v[24:27], v[162:165], v[206:209], v[24:27]
	v_mfma_f32_16x16x32_bf16 v[12:15], v[128:131], v[214:217], v[12:15]
	v_mfma_f32_16x16x32_bf16 v[8:11], v[162:165], v[214:217], v[8:11]
	v_mfma_f32_16x16x32_bf16 v[60:63], v[132:135], v[194:197], v[60:63]
	v_mfma_f32_16x16x32_bf16 v[56:59], v[166:169], v[194:197], v[56:59]
	v_mfma_f32_16x16x32_bf16 v[44:47], v[132:135], v[202:205], v[44:47]
	v_mfma_f32_16x16x32_bf16 v[40:43], v[166:169], v[202:205], v[40:43]
	v_mfma_f32_16x16x32_bf16 v[28:31], v[132:135], v[210:213], v[28:31]
	v_mfma_f32_16x16x32_bf16 v[24:27], v[166:169], v[210:213], v[24:27]
	v_mfma_f32_16x16x32_bf16 v[12:15], v[132:135], v[218:221], v[12:15]
	v_mfma_f32_16x16x32_bf16 v[8:11], v[166:169], v[218:221], v[8:11]
	v_mfma_f32_16x16x32_bf16 v[52:55], v[174:177], v[190:193], v[52:55]
	v_mfma_f32_16x16x32_bf16 v[48:51], v[182:185], v[190:193], v[48:51]
	v_mfma_f32_16x16x32_bf16 v[36:39], v[174:177], v[198:201], v[36:39]
	v_mfma_f32_16x16x32_bf16 v[32:35], v[182:185], v[198:201], v[32:35]
	v_mfma_f32_16x16x32_bf16 v[20:23], v[174:177], v[206:209], v[20:23]
	v_mfma_f32_16x16x32_bf16 v[16:19], v[182:185], v[206:209], v[16:19]
	v_mfma_f32_16x16x32_bf16 v[4:7], v[174:177], v[214:217], v[4:7]
	v_mfma_f32_16x16x32_bf16 v[0:3], v[182:185], v[214:217], v[0:3]
	v_mfma_f32_16x16x32_bf16 v[52:55], v[178:181], v[194:197], v[52:55]
	v_mfma_f32_16x16x32_bf16 v[48:51], v[186:189], v[194:197], v[48:51]
	v_mfma_f32_16x16x32_bf16 v[36:39], v[178:181], v[202:205], v[36:39]
	v_mfma_f32_16x16x32_bf16 v[32:35], v[186:189], v[202:205], v[32:35]
	v_mfma_f32_16x16x32_bf16 v[20:23], v[178:181], v[210:213], v[20:23]
	v_mfma_f32_16x16x32_bf16 v[16:19], v[186:189], v[210:213], v[16:19]
	v_mfma_f32_16x16x32_bf16 v[4:7], v[178:181], v[218:221], v[4:7]
	v_mfma_f32_16x16x32_bf16 v[0:3], v[186:189], v[218:221], v[0:3]
	s_setprio 0
	s_barrier
	s_add_i32 s21, s21, 2
	s_add_u32 s4, s4, 0x100
	s_addc_u32 s5, s5, 0
	s_add_u32 s17, s17, 0x100
	s_addc_u32 s20, s20, 0
	s_cmp_gt_u32 s21, 13
	s_cbranch_scc0 .LBB0_101
	s_lshl_b32 s0, s16, 8
	s_add_i32 s0, s0, s81
	s_and_b32 s1, s2, -2
	s_cmp_lg_u32 s1, 6
	s_cselect_b64 s[4:5], -1, 0
	s_add_i32 s1, s2, -12
	s_cmp_gt_u32 s1, -11
	s_cselect_b64 s[6:7], -1, 0
	s_and_b64 s[6:7], s[6:7], s[4:5]
	v_or_b32_e32 v162, s0, v147
	s_mov_b64 s[4:5], -1
	s_and_b64 vcc, exec, s[6:7]
	s_cbranch_vccz .LBB0_188
	s_cmp_gt_u32 s2, 5
	s_cbranch_scc0 .LBB0_185
	v_cmp_lt_i32_e64 s[6:7], s97, v162
	s_and_saveexec_b64 s[4:5], s[6:7]
	s_xor_b64 s[4:5], exec, s[4:5]
	v_add_u32_e32 v128, 0xffffc000, v162
	v_lshrrev_b32_e32 v128, 3, v128
	v_mad_u64_u32 v[166:167], s[18:19], v128, 38, v[148:149]
	s_or_saveexec_b64 s[4:5], s[4:5]
	s_ashr_i32 s0, s0, 13
	s_mul_i32 s18, s0, 30
	s_add_i32 s1, s18, 30
	s_xor_b64 exec, exec, s[4:5]
	v_add_u32_e32 v166, s1, v162
	s_or_b64 exec, exec, s[4:5]
	v_mul_f32_e32 v132, 0xbfb8aa3b, v112
	v_exp_f32_e32 v132, v132
	v_mul_f32_e32 v133, 0xbfb8aa3b, v113
	v_exp_f32_e32 v133, v133
	v_mul_f32_e32 v128, 0xbfb8aa3b, v116
	v_add_f32_e32 v132, 1.0, v132
	v_rcp_f32_e32 v168, v132
	v_add_f32_e32 v132, 1.0, v133
	v_mul_f32_e32 v133, 0xbfb8aa3b, v114
	v_mul_f32_e32 v129, 0xbfb8aa3b, v117
	v_mul_f32_e32 v130, 0xbfb8aa3b, v118
	v_mul_f32_e32 v131, 0xbfb8aa3b, v119
	v_exp_f32_e32 v133, v133
	v_mul_f32_e32 v134, 0xbfb8aa3b, v115
	v_exp_f32_e32 v128, v128
	v_exp_f32_e32 v129, v129
	v_exp_f32_e32 v130, v130
	v_exp_f32_e32 v131, v131
	v_exp_f32_e32 v134, v134
	s_lshl_b32 s0, s2, 7
	s_lshl_b32 s14, s2, 8
	s_and_b32 s3, s16, 31
	v_rcp_f32_e32 v169, v132
	v_add_f32_e32 v132, 1.0, v133
	s_cmp_eq_u32 s3, 31
	v_add_f32_e32 v128, 1.0, v128
	v_add_f32_e32 v129, 1.0, v129
	v_add_f32_e32 v130, 1.0, v130
	v_add_f32_e32 v131, 1.0, v131
	v_rcp_f32_e32 v174, v132
	v_add_f32_e32 v132, 1.0, v134
	s_cselect_b64 s[4:5], -1, 0
	s_cmp_gt_i32 s16, 63
	v_rcp_f32_e32 v128, v128
	v_rcp_f32_e32 v129, v129
	v_rcp_f32_e32 v130, v130
	v_rcp_f32_e32 v131, v131
	v_rcp_f32_e32 v175, v132
	s_cselect_b64 s[20:21], -1, 0
	v_ashrrev_i32_e32 v167, 31, v166
	s_or_b64 s[20:21], s[20:21], s[4:5]
	v_lshl_add_u64 v[164:165], v[152:153], 0, s[14:15]
	v_lshlrev_b64 v[166:167], 10, v[166:167]
	v_cndmask_b32_e64 v144, 0, 1, s[20:21]
	v_pk_mul_f32 v[132:133], v[124:125], v[128:129]
	v_pk_mul_f32 v[134:135], v[126:127], v[130:131]
	v_pk_mul_f32 v[128:129], v[120:121], v[168:169]
	v_pk_mul_f32 v[130:131], v[122:123], v[174:175]
	v_lshl_add_u64 v[166:167], v[164:165], 0, v[166:167]
	v_cmp_ne_u32_e64 s[4:5], 1, v144
	s_andn2_b64 vcc, exec, s[20:21]
	v_cvt_pk_bf16_f32 v174, v132, v133
	v_cvt_pk_bf16_f32 v175, v134, v135
	v_cvt_pk_bf16_f32 v176, v128, v129
	v_cvt_pk_bf16_f32 v177, v130, v131
	global_store_dwordx4 v[166:167], v[174:177], off offset:-2048
	s_cbranch_vccnz .LBB0_114
	v_mov_b64_e32 v[166:167], -1
	s_and_saveexec_b64 s[20:21], s[6:7]
	v_add_u32_e32 v144, 0xffffc000, v162
	v_lshrrev_b32_e32 v144, 3, v144
	v_mad_u64_u32 v[166:167], s[6:7], v144, 30, v[150:151]
	v_lshlrev_b64 v[166:167], 9, v[166:167]
	v_lshl_add_u64 v[166:167], v[166:167], 0, s[34:35]
	s_or_b64 exec, exec, s[20:21]
	v_cmp_lt_i64_e32 vcc, -1, v[166:167]
	s_and_saveexec_b64 s[6:7], vcc
	s_cbranch_execz .LBB0_113
	v_readlane_b32 s84, v247, 20
	v_readlane_b32 s86, v247, 22
	v_readlane_b32 s87, v247, 23
	v_add_u32_e32 v144, s0, v146
	v_readlane_b32 s85, v247, 21
	v_lshl_add_u64 v[166:167], v[166:167], 2, s[86:87]
	v_lshl_add_u64 v[166:167], v[144:145], 2, v[166:167]
	global_store_dwordx4 v[166:167], v[132:135], off offset:-4096
	global_store_dwordx4 v[166:167], v[128:131], off offset:-4080

.LBB0_574:
	ds_read_b128 v[148:151], v110
	ds_read_b128 v[152:155], v110 offset:1024
	ds_read_b128 v[156:159], v110 offset:2048
	ds_read_b128 v[160:163], v110 offset:3072
	ds_read_b128 v[164:167], v111
	ds_read_b128 v[168:171], v111 offset:1024
	ds_read_b128 v[172:175], v111 offset:2048
	ds_read_b128 v[176:179], v111 offset:3072
	s_add_u32 s14, s10, s12
	s_addc_u32 s15, s11, s13
	s_add_u32 s14, s14, 0xba00100
	s_addc_u32 s15, s15, 0
	s_add_u32 s46, s25, s12
	s_addc_u32 s47, s26, s13
	s_cmpk_eq_i32 s12, 0x300
	s_cselect_b32 s17, s7, s15
	s_cselect_b32 s16, s6, s14
	s_cselect_b32 s15, s5, s47
	s_cselect_b32 s14, s4, s46
	s_mov_b32 m0, s28
	v_lshl_add_u64 v[212:213], v[104:105], 0, s[12:13]
	ds_read_b128 v[180:183], v144
	ds_read_b128 v[184:187], v144 offset:1024
	ds_read_b128 v[188:191], v144 offset:2048
	ds_read_b128 v[192:195], v144 offset:3072
	ds_read_b128 v[196:199], v144 offset:4096
	ds_read_b128 v[200:203], v144 offset:5120
	ds_read_b128 v[204:207], v144 offset:6144
	ds_read_b128 v[208:211], v144 offset:7168
	global_load_lds_dwordx4 v[212:213], off
	v_lshl_add_u64 v[212:213], v[106:107], 0, s[12:13]
	s_mov_b32 m0, s29
	s_nop 0
	global_load_lds_dwordx4 v[212:213], off
	s_waitcnt vmcnt(8)
	s_waitcnt lgkmcnt(0)
	s_barrier
	s_setprio 1
	v_mfma_f32_16x16x32_bf16 v[140:143], v[148:151], v[180:183], v[140:143]
	v_mfma_f32_16x16x32_bf16 v[136:139], v[156:159], v[180:183], v[136:139]
	v_mfma_f32_16x16x32_bf16 v[124:127], v[148:151], v[188:191], v[124:127]
	v_mfma_f32_16x16x32_bf16 v[120:123], v[156:159], v[188:191], v[120:123]
	v_mfma_f32_16x16x32_bf16 v[100:103], v[148:151], v[196:199], v[100:103]
	v_mfma_f32_16x16x32_bf16 v[96:99], v[156:159], v[196:199], v[96:99]
	v_mfma_f32_16x16x32_bf16 v[76:79], v[148:151], v[204:207], v[76:79]
	v_mfma_f32_16x16x32_bf16 v[72:75], v[156:159], v[204:207], v[72:75]
	v_mfma_f32_16x16x32_bf16 v[140:143], v[152:155], v[184:187], v[140:143]
	v_mfma_f32_16x16x32_bf16 v[136:139], v[160:163], v[184:187], v[136:139]
	v_mfma_f32_16x16x32_bf16 v[124:127], v[152:155], v[192:195], v[124:127]
	v_mfma_f32_16x16x32_bf16 v[120:123], v[160:163], v[192:195], v[120:123]
	v_mfma_f32_16x16x32_bf16 v[100:103], v[152:155], v[200:203], v[100:103]
	v_mfma_f32_16x16x32_bf16 v[96:99], v[160:163], v[200:203], v[96:99]
	v_mfma_f32_16x16x32_bf16 v[76:79], v[152:155], v[208:211], v[76:79]
	v_mfma_f32_16x16x32_bf16 v[72:75], v[160:163], v[208:211], v[72:75]
	v_mfma_f32_16x16x32_bf16 v[132:135], v[164:167], v[180:183], v[132:135]
	v_mfma_f32_16x16x32_bf16 v[128:131], v[172:175], v[180:183], v[128:131]
	v_mfma_f32_16x16x32_bf16 v[116:119], v[164:167], v[188:191], v[116:119]
	v_mfma_f32_16x16x32_bf16 v[112:115], v[172:175], v[188:191], v[112:115]
	v_mfma_f32_16x16x32_bf16 v[84:87], v[164:167], v[196:199], v[84:87]
	v_mfma_f32_16x16x32_bf16 v[80:83], v[172:175], v[196:199], v[80:83]
	v_mfma_f32_16x16x32_bf16 v[68:71], v[164:167], v[204:207], v[68:71]
	v_mfma_f32_16x16x32_bf16 v[64:67], v[172:175], v[204:207], v[64:67]
	v_mfma_f32_16x16x32_bf16 v[132:135], v[168:171], v[184:187], v[132:135]
	v_mfma_f32_16x16x32_bf16 v[128:131], v[176:179], v[184:187], v[128:131]
	v_mfma_f32_16x16x32_bf16 v[116:119], v[168:171], v[192:195], v[116:119]
	v_mfma_f32_16x16x32_bf16 v[112:115], v[176:179], v[192:195], v[112:115]
	v_mfma_f32_16x16x32_bf16 v[84:87], v[168:171], v[200:203], v[84:87]
	v_mfma_f32_16x16x32_bf16 v[80:83], v[176:179], v[200:203], v[80:83]
	v_mfma_f32_16x16x32_bf16 v[68:71], v[168:171], v[208:211], v[68:71]
	v_mfma_f32_16x16x32_bf16 v[64:67], v[176:179], v[208:211], v[64:67]
	s_setprio 0
	s_barrier
	s_mov_b32 m0, s34
	v_lshl_add_u64 v[212:213], s[14:15], 0, v[92:93]
	s_add_u32 s46, s14, 0x20000
	ds_read_b128 v[180:183], v144 offset:16384
	ds_read_b128 v[184:187], v144 offset:17408
	ds_read_b128 v[188:191], v144 offset:18432
	ds_read_b128 v[192:195], v144 offset:19456
	ds_read_b128 v[196:199], v144 offset:20480
	ds_read_b128 v[200:203], v144 offset:21504
	ds_read_b128 v[204:207], v144 offset:22528
	ds_read_b128 v[208:211], v144 offset:23552
	global_load_lds_dwordx4 v[212:213], off
	v_lshl_add_u64 v[214:215], s[14:15], 0, v[88:89]
	s_mov_b32 m0, s35
	s_addc_u32 s47, s15, 0
	global_load_lds_dwordx4 v[214:215], off
	v_lshl_add_u64 v[216:217], s[46:47], 0, v[92:93]
	s_mov_b32 m0, s40
	v_lshl_add_u64 v[218:219], s[16:17], 0, v[90:91]
	global_load_lds_dwordx4 v[216:217], off
	v_lshl_add_u64 v[216:217], s[46:47], 0, v[88:89]
	s_mov_b32 m0, s41
	s_nop 0
	global_load_lds_dwordx4 v[216:217], off
	v_lshl_add_u64 v[216:217], s[16:17], 0, v[94:95]
	s_mov_b32 m0, s3
	s_nop 0
	global_load_lds_dwordx4 v[216:217], off
	s_mov_b32 m0, s19
	s_nop 0
	global_load_lds_dwordx4 v[218:219], off
	s_waitcnt vmcnt(8)
	s_waitcnt lgkmcnt(0)
	s_barrier
	s_setprio 1
	v_mfma_f32_16x16x32_bf16 v[60:63], v[148:151], v[180:183], v[60:63]
	v_mfma_f32_16x16x32_bf16 v[56:59], v[156:159], v[180:183], v[56:59]
	v_mfma_f32_16x16x32_bf16 v[44:47], v[148:151], v[188:191], v[44:47]
	v_mfma_f32_16x16x32_bf16 v[40:43], v[156:159], v[188:191], v[40:43]
	v_mfma_f32_16x16x32_bf16 v[28:31], v[148:151], v[196:199], v[28:31]
	v_mfma_f32_16x16x32_bf16 v[24:27], v[156:159], v[196:199], v[24:27]
	v_mfma_f32_16x16x32_bf16 v[12:15], v[148:151], v[204:207], v[12:15]
	v_mfma_f32_16x16x32_bf16 v[8:11], v[156:159], v[204:207], v[8:11]
	v_mfma_f32_16x16x32_bf16 v[60:63], v[152:155], v[184:187], v[60:63]
	v_mfma_f32_16x16x32_bf16 v[56:59], v[160:163], v[184:187], v[56:59]
	v_mfma_f32_16x16x32_bf16 v[44:47], v[152:155], v[192:195], v[44:47]
	v_mfma_f32_16x16x32_bf16 v[40:43], v[160:163], v[192:195], v[40:43]
	v_mfma_f32_16x16x32_bf16 v[28:31], v[152:155], v[200:203], v[28:31]
	v_mfma_f32_16x16x32_bf16 v[24:27], v[160:163], v[200:203], v[24:27]
	v_mfma_f32_16x16x32_bf16 v[12:15], v[152:155], v[208:211], v[12:15]
	v_mfma_f32_16x16x32_bf16 v[8:11], v[160:163], v[208:211], v[8:11]
	v_mfma_f32_16x16x32_bf16 v[52:55], v[164:167], v[180:183], v[52:55]
	v_mfma_f32_16x16x32_bf16 v[48:51], v[172:175], v[180:183], v[48:51]
	v_mfma_f32_16x16x32_bf16 v[36:39], v[164:167], v[188:191], v[36:39]
	v_mfma_f32_16x16x32_bf16 v[32:35], v[172:175], v[188:191], v[32:35]
	v_mfma_f32_16x16x32_bf16 v[20:23], v[164:167], v[196:199], v[20:23]
	v_mfma_f32_16x16x32_bf16 v[16:19], v[172:175], v[196:199], v[16:19]
	v_mfma_f32_16x16x32_bf16 v[4:7], v[164:167], v[204:207], v[4:7]
	v_mfma_f32_16x16x32_bf16 v[0:3], v[172:175], v[204:207], v[0:3]
	v_mfma_f32_16x16x32_bf16 v[52:55], v[168:171], v[184:187], v[52:55]
	v_mfma_f32_16x16x32_bf16 v[48:51], v[176:179], v[184:187], v[48:51]
	v_mfma_f32_16x16x32_bf16 v[36:39], v[168:171], v[192:195], v[36:39]
	v_mfma_f32_16x16x32_bf16 v[32:35], v[176:179], v[192:195], v[32:35]
	v_mfma_f32_16x16x32_bf16 v[20:23], v[168:171], v[200:203], v[20:23]
	v_mfma_f32_16x16x32_bf16 v[16:19], v[176:179], v[200:203], v[16:19]
	v_mfma_f32_16x16x32_bf16 v[4:7], v[168:171], v[208:211], v[4:7]
	v_mfma_f32_16x16x32_bf16 v[0:3], v[176:179], v[208:211], v[0:3]
	s_setprio 0
	s_barrier
	ds_read_b128 v[148:151], v145
	ds_read_b128 v[152:155], v145 offset:1024
	ds_read_b128 v[156:159], v145 offset:2048
	ds_read_b128 v[160:163], v145 offset:3072
	ds_read_b128 v[164:167], v146
	ds_read_b128 v[168:171], v146 offset:1024
	ds_read_b128 v[172:175], v146 offset:2048
	ds_read_b128 v[176:179], v146 offset:3072
	s_add_u32 s16, s16, 0x20000
	s_addc_u32 s17, s17, 0
	s_mov_b32 m0, s20
	v_lshl_add_u64 v[220:221], s[16:17], 0, v[94:95]
	ds_read_b128 v[180:183], v144 offset:32768
	ds_read_b128 v[184:187], v144 offset:33792
	ds_read_b128 v[188:191], v144 offset:34816
	ds_read_b128 v[192:195], v144 offset:35840
	ds_read_b128 v[196:199], v144 offset:36864
	ds_read_b128 v[200:203], v144 offset:37888
	ds_read_b128 v[204:207], v144 offset:38912
	ds_read_b128 v[208:211], v144 offset:39936
	global_load_lds_dwordx4 v[220:221], off
	v_lshl_add_u64 v[220:221], s[16:17], 0, v[90:91]
	s_mov_b32 m0, s21
	s_nop 0
	global_load_lds_dwordx4 v[220:221], off
	s_waitcnt vmcnt(8)
	s_waitcnt lgkmcnt(0)
	s_barrier
	s_setprio 1
	v_mfma_f32_16x16x32_bf16 v[140:143], v[148:151], v[180:183], v[140:143]
	v_mfma_f32_16x16x32_bf16 v[136:139], v[156:159], v[180:183], v[136:139]
	v_mfma_f32_16x16x32_bf16 v[124:127], v[148:151], v[188:191], v[124:127]
	v_mfma_f32_16x16x32_bf16 v[120:123], v[156:159], v[188:191], v[120:123]
	v_mfma_f32_16x16x32_bf16 v[100:103], v[148:151], v[196:199], v[100:103]
	v_mfma_f32_16x16x32_bf16 v[96:99], v[156:159], v[196:199], v[96:99]
	v_mfma_f32_16x16x32_bf16 v[76:79], v[148:151], v[204:207], v[76:79]
	v_mfma_f32_16x16x32_bf16 v[72:75], v[156:159], v[204:207], v[72:75]
	v_mfma_f32_16x16x32_bf16 v[140:143], v[152:155], v[184:187], v[140:143]
	v_mfma_f32_16x16x32_bf16 v[136:139], v[160:163], v[184:187], v[136:139]
	v_mfma_f32_16x16x32_bf16 v[124:127], v[152:155], v[192:195], v[124:127]
	v_mfma_f32_16x16x32_bf16 v[120:123], v[160:163], v[192:195], v[120:123]
	v_mfma_f32_16x16x32_bf16 v[100:103], v[152:155], v[200:203], v[100:103]
	v_mfma_f32_16x16x32_bf16 v[96:99], v[160:163], v[200:203], v[96:99]
	v_mfma_f32_16x16x32_bf16 v[76:79], v[152:155], v[208:211], v[76:79]
	v_mfma_f32_16x16x32_bf16 v[72:75], v[160:163], v[208:211], v[72:75]
	v_mfma_f32_16x16x32_bf16 v[132:135], v[164:167], v[180:183], v[132:135]
	v_mfma_f32_16x16x32_bf16 v[128:131], v[172:175], v[180:183], v[128:131]
	v_mfma_f32_16x16x32_bf16 v[116:119], v[164:167], v[188:191], v[116:119]
	v_mfma_f32_16x16x32_bf16 v[112:115], v[172:175], v[188:191], v[112:115]
	v_mfma_f32_16x16x32_bf16 v[84:87], v[164:167], v[196:199], v[84:87]
	v_mfma_f32_16x16x32_bf16 v[80:83], v[172:175], v[196:199], v[80:83]
	v_mfma_f32_16x16x32_bf16 v[68:71], v[164:167], v[204:207], v[68:71]
	v_mfma_f32_16x16x32_bf16 v[64:67], v[172:175], v[204:207], v[64:67]
	v_mfma_f32_16x16x32_bf16 v[132:135], v[168:171], v[184:187], v[132:135]
	v_mfma_f32_16x16x32_bf16 v[128:131], v[176:179], v[184:187], v[128:131]
	v_mfma_f32_16x16x32_bf16 v[116:119], v[168:171], v[192:195], v[116:119]
	v_mfma_f32_16x16x32_bf16 v[112:115], v[176:179], v[192:195], v[112:115]
	v_mfma_f32_16x16x32_bf16 v[84:87], v[168:171], v[200:203], v[84:87]
	v_mfma_f32_16x16x32_bf16 v[80:83], v[176:179], v[200:203], v[80:83]
	v_mfma_f32_16x16x32_bf16 v[68:71], v[168:171], v[208:211], v[68:71]
	v_mfma_f32_16x16x32_bf16 v[64:67], v[176:179], v[208:211], v[64:67]
	s_setprio 0
	s_barrier
	s_mov_b32 m0, s42
	v_lshl_add_u64 v[212:213], v[212:213], 0, s[8:9]
	s_add_u32 s14, s14, 0x20080
	ds_read_b128 v[180:183], v144 offset:49152
	ds_read_b128 v[184:187], v144 offset:50176
	ds_read_b128 v[188:191], v144 offset:51200
	ds_read_b128 v[192:195], v144 offset:52224
	ds_read_b128 v[196:199], v144 offset:53248
	ds_read_b128 v[200:203], v144 offset:54272
	ds_read_b128 v[204:207], v144 offset:55296
	ds_read_b128 v[208:211], v144 offset:56320
	global_load_lds_dwordx4 v[212:213], off
	v_lshl_add_u64 v[212:213], v[214:215], 0, s[8:9]
	s_mov_b32 m0, s43
	s_addc_u32 s15, s15, 0
	global_load_lds_dwordx4 v[212:213], off
	v_lshl_add_u64 v[212:213], s[14:15], 0, v[92:93]
	s_mov_b32 m0, s44
	s_nop 0
	global_load_lds_dwordx4 v[212:213], off
	v_lshl_add_u64 v[212:213], s[14:15], 0, v[88:89]
	s_mov_b32 m0, s45
	s_nop 0
	global_load_lds_dwordx4 v[212:213], off
	v_lshl_add_u64 v[212:213], v[216:217], 0, s[8:9]
	s_mov_b32 m0, s23
	s_nop 0
	global_load_lds_dwordx4 v[212:213], off
	v_lshl_add_u64 v[212:213], v[218:219], 0, s[8:9]
	s_mov_b32 m0, s24
	s_nop 0
	global_load_lds_dwordx4 v[212:213], off
	s_waitcnt vmcnt(8)
	s_waitcnt lgkmcnt(0)
	s_barrier
	s_setprio 1
	v_mfma_f32_16x16x32_bf16 v[60:63], v[148:151], v[180:183], v[60:63]
	v_mfma_f32_16x16x32_bf16 v[56:59], v[156:159], v[180:183], v[56:59]
	v_mfma_f32_16x16x32_bf16 v[44:47], v[148:151], v[188:191], v[44:47]
	v_mfma_f32_16x16x32_bf16 v[40:43], v[156:159], v[188:191], v[40:43]
	v_mfma_f32_16x16x32_bf16 v[28:31], v[148:151], v[196:199], v[28:31]
	v_mfma_f32_16x16x32_bf16 v[24:27], v[156:159], v[196:199], v[24:27]
	v_mfma_f32_16x16x32_bf16 v[12:15], v[148:151], v[204:207], v[12:15]
	v_mfma_f32_16x16x32_bf16 v[8:11], v[156:159], v[204:207], v[8:11]
	v_mfma_f32_16x16x32_bf16 v[60:63], v[152:155], v[184:187], v[60:63]
	v_mfma_f32_16x16x32_bf16 v[56:59], v[160:163], v[184:187], v[56:59]
	v_mfma_f32_16x16x32_bf16 v[44:47], v[152:155], v[192:195], v[44:47]
	v_mfma_f32_16x16x32_bf16 v[40:43], v[160:163], v[192:195], v[40:43]
	v_mfma_f32_16x16x32_bf16 v[28:31], v[152:155], v[200:203], v[28:31]
	v_mfma_f32_16x16x32_bf16 v[24:27], v[160:163], v[200:203], v[24:27]
	v_mfma_f32_16x16x32_bf16 v[12:15], v[152:155], v[208:211], v[12:15]
	v_mfma_f32_16x16x32_bf16 v[8:11], v[160:163], v[208:211], v[8:11]
	v_mfma_f32_16x16x32_bf16 v[52:55], v[164:167], v[180:183], v[52:55]
	v_mfma_f32_16x16x32_bf16 v[48:51], v[172:175], v[180:183], v[48:51]
	v_mfma_f32_16x16x32_bf16 v[36:39], v[164:167], v[188:191], v[36:39]
	v_mfma_f32_16x16x32_bf16 v[32:35], v[172:175], v[188:191], v[32:35]
	v_mfma_f32_16x16x32_bf16 v[20:23], v[164:167], v[196:199], v[20:23]
	v_mfma_f32_16x16x32_bf16 v[16:19], v[172:175], v[196:199], v[16:19]
	v_mfma_f32_16x16x32_bf16 v[4:7], v[164:167], v[204:207], v[4:7]
	v_mfma_f32_16x16x32_bf16 v[0:3], v[172:175], v[204:207], v[0:3]
	v_mfma_f32_16x16x32_bf16 v[52:55], v[168:171], v[184:187], v[52:55]
	v_mfma_f32_16x16x32_bf16 v[48:51], v[176:179], v[184:187], v[48:51]
	v_mfma_f32_16x16x32_bf16 v[36:39], v[168:171], v[192:195], v[36:39]
	v_mfma_f32_16x16x32_bf16 v[32:35], v[176:179], v[192:195], v[32:35]
	v_mfma_f32_16x16x32_bf16 v[20:23], v[168:171], v[200:203], v[20:23]
	v_mfma_f32_16x16x32_bf16 v[16:19], v[176:179], v[200:203], v[16:19]
	v_mfma_f32_16x16x32_bf16 v[4:7], v[168:171], v[208:211], v[4:7]
	v_mfma_f32_16x16x32_bf16 v[0:3], v[176:179], v[208:211], v[0:3]
	s_setprio 0
	s_barrier
	s_add_i32 s27, s27, 2
	s_add_u32 s12, s12, 0x100
	s_addc_u32 s13, s13, 0
	s_cmp_gt_u32 s27, 5
	s_cbranch_scc0 .LBB0_574
	s_cmpk_lt_u32 s18, 0x100
	s_cbranch_scc0 .LBB0_577
	s_barrier

.LBB0_654:
	s_add_u32 s40, s58, s34
	s_addc_u32 s41, s59, s35
	s_add_u32 s40, s40, 0xec00100
	s_addc_u32 s41, s41, 0
	s_add_u32 s63, s60, s34
	s_addc_u32 s64, s61, s35
	s_add_i32 s65, 0, 0x10000
	s_cmpk_eq_i32 s34, 0x700
	s_cselect_b32 s43, s23, s41
	s_cselect_b32 s42, s22, s40
	s_cselect_b32 s41, s19, s64
	s_cselect_b32 s40, s18, s63
	s_add_i32 s63, 0, 0x14000
	v_add_u32_e32 v158, s65, v144
	v_add_u32_e32 v174, s63, v144
	ds_read_b128 v[146:149], v158
	ds_read_b128 v[150:153], v158 offset:1024
	ds_read_b128 v[154:157], v158 offset:2048
	ds_read_b128 v[158:161], v158 offset:3072
	ds_read_b128 v[162:165], v174
	ds_read_b128 v[166:169], v174 offset:1024
	ds_read_b128 v[170:173], v174 offset:2048
	ds_read_b128 v[174:177], v174 offset:3072
	v_lshl_add_u64 v[210:211], v[136:137], 0, s[34:35]
	s_add_i32 m0, s17, 0xc000
	ds_read_b128 v[178:181], v145
	ds_read_b128 v[182:185], v145 offset:1024
	ds_read_b128 v[186:189], v145 offset:2048
	ds_read_b128 v[190:193], v145 offset:3072
	ds_read_b128 v[194:197], v145 offset:4096
	ds_read_b128 v[198:201], v145 offset:5120
	ds_read_b128 v[202:205], v145 offset:6144
	ds_read_b128 v[206:209], v145 offset:7168
	global_load_lds_dwordx4 v[210:211], off
	v_lshl_add_u64 v[210:211], v[138:139], 0, s[34:35]
	s_add_i32 m0, s17, 0xe000
	s_nop 0
	global_load_lds_dwordx4 v[210:211], off
	s_waitcnt vmcnt(8)
	s_waitcnt lgkmcnt(0)
	s_barrier
	s_setprio 1
	v_mfma_f32_16x16x32_bf16 v[124:127], v[146:149], v[178:181], v[124:127]
	v_mfma_f32_16x16x32_bf16 v[120:123], v[154:157], v[178:181], v[120:123]
	v_mfma_f32_16x16x32_bf16 v[116:119], v[146:149], v[186:189], v[116:119]
	v_mfma_f32_16x16x32_bf16 v[108:111], v[154:157], v[186:189], v[108:111]
	v_mfma_f32_16x16x32_bf16 v[100:103], v[146:149], v[194:197], v[100:103]
	v_mfma_f32_16x16x32_bf16 v[92:95], v[154:157], v[194:197], v[92:95]
	v_mfma_f32_16x16x32_bf16 v[84:87], v[146:149], v[202:205], v[84:87]
	v_mfma_f32_16x16x32_bf16 v[76:79], v[154:157], v[202:205], v[76:79]
	v_mfma_f32_16x16x32_bf16 v[124:127], v[150:153], v[182:185], v[124:127]
	v_mfma_f32_16x16x32_bf16 v[120:123], v[158:161], v[182:185], v[120:123]
	v_mfma_f32_16x16x32_bf16 v[116:119], v[150:153], v[190:193], v[116:119]
	v_mfma_f32_16x16x32_bf16 v[108:111], v[158:161], v[190:193], v[108:111]
	v_mfma_f32_16x16x32_bf16 v[100:103], v[150:153], v[198:201], v[100:103]
	v_mfma_f32_16x16x32_bf16 v[92:95], v[158:161], v[198:201], v[92:95]
	v_mfma_f32_16x16x32_bf16 v[84:87], v[150:153], v[206:209], v[84:87]
	v_mfma_f32_16x16x32_bf16 v[76:79], v[158:161], v[206:209], v[76:79]
	v_mfma_f32_16x16x32_bf16 v[112:115], v[162:165], v[178:181], v[112:115]
	v_mfma_f32_16x16x32_bf16 v[104:107], v[170:173], v[178:181], v[104:107]
	v_mfma_f32_16x16x32_bf16 v[96:99], v[162:165], v[186:189], v[96:99]
	v_mfma_f32_16x16x32_bf16 v[88:91], v[170:173], v[186:189], v[88:91]
	v_mfma_f32_16x16x32_bf16 v[80:83], v[162:165], v[194:197], v[80:83]
	v_mfma_f32_16x16x32_bf16 v[72:75], v[170:173], v[194:197], v[72:75]
	v_mfma_f32_16x16x32_bf16 v[68:71], v[162:165], v[202:205], v[68:71]
	v_mfma_f32_16x16x32_bf16 v[64:67], v[170:173], v[202:205], v[64:67]
	v_mfma_f32_16x16x32_bf16 v[112:115], v[166:169], v[182:185], v[112:115]
	v_mfma_f32_16x16x32_bf16 v[104:107], v[174:177], v[182:185], v[104:107]
	v_mfma_f32_16x16x32_bf16 v[96:99], v[166:169], v[190:193], v[96:99]
	v_mfma_f32_16x16x32_bf16 v[88:91], v[174:177], v[190:193], v[88:91]
	v_mfma_f32_16x16x32_bf16 v[80:83], v[166:169], v[198:201], v[80:83]
	v_mfma_f32_16x16x32_bf16 v[72:75], v[174:177], v[198:201], v[72:75]
	v_mfma_f32_16x16x32_bf16 v[68:71], v[166:169], v[206:209], v[68:71]
	v_mfma_f32_16x16x32_bf16 v[64:67], v[174:177], v[206:209], v[64:67]
	s_setprio 0
	s_barrier
	s_add_i32 s64, s65, s46
	v_lshl_add_u64 v[210:211], s[40:41], 0, v[128:129]
	s_mov_b32 m0, s64
	ds_read_b128 v[178:181], v145 offset:16384
	ds_read_b128 v[182:185], v145 offset:17408
	ds_read_b128 v[186:189], v145 offset:18432
	ds_read_b128 v[190:193], v145 offset:19456
	ds_read_b128 v[194:197], v145 offset:20480
	ds_read_b128 v[198:201], v145 offset:21504
	ds_read_b128 v[202:205], v145 offset:22528
	ds_read_b128 v[206:209], v145 offset:23552
	global_load_lds_dwordx4 v[210:211], off
	s_add_i32 m0, s64, 0x2000
	s_add_u32 s64, s40, 0x40000
	v_lshl_add_u64 v[212:213], s[40:41], 0, v[134:135]
	s_addc_u32 s65, s41, 0
	s_add_i32 s63, s63, s46
	global_load_lds_dwordx4 v[212:213], off
	v_lshl_add_u64 v[214:215], s[64:65], 0, v[128:129]
	s_mov_b32 m0, s63
	v_lshl_add_u64 v[216:217], s[42:43], 0, v[132:133]
	global_load_lds_dwordx4 v[214:215], off
	v_lshl_add_u64 v[214:215], s[64:65], 0, v[134:135]
	s_add_i32 m0, s63, 0x2000
	s_nop 0
	global_load_lds_dwordx4 v[214:215], off
	v_lshl_add_u64 v[214:215], s[42:43], 0, v[130:131]
	s_mov_b32 m0, s17
	s_nop 0
	global_load_lds_dwordx4 v[214:215], off
	s_mov_b32 m0, s47
	s_nop 0
	global_load_lds_dwordx4 v[216:217], off
	s_waitcnt vmcnt(8)
	s_waitcnt lgkmcnt(0)
	s_barrier
	s_setprio 1
	v_mfma_f32_16x16x32_bf16 v[60:63], v[146:149], v[178:181], v[60:63]
	v_mfma_f32_16x16x32_bf16 v[56:59], v[154:157], v[178:181], v[56:59]
	v_mfma_f32_16x16x32_bf16 v[52:55], v[146:149], v[186:189], v[52:55]
	v_mfma_f32_16x16x32_bf16 v[44:47], v[154:157], v[186:189], v[44:47]
	v_mfma_f32_16x16x32_bf16 v[36:39], v[146:149], v[194:197], v[36:39]
	v_mfma_f32_16x16x32_bf16 v[28:31], v[154:157], v[194:197], v[28:31]
	v_mfma_f32_16x16x32_bf16 v[20:23], v[146:149], v[202:205], v[20:23]
	v_mfma_f32_16x16x32_bf16 v[12:15], v[154:157], v[202:205], v[12:15]
	v_mfma_f32_16x16x32_bf16 v[60:63], v[150:153], v[182:185], v[60:63]
	v_mfma_f32_16x16x32_bf16 v[56:59], v[158:161], v[182:185], v[56:59]
	v_mfma_f32_16x16x32_bf16 v[52:55], v[150:153], v[190:193], v[52:55]
	v_mfma_f32_16x16x32_bf16 v[44:47], v[158:161], v[190:193], v[44:47]
	v_mfma_f32_16x16x32_bf16 v[36:39], v[150:153], v[198:201], v[36:39]
	v_mfma_f32_16x16x32_bf16 v[28:31], v[158:161], v[198:201], v[28:31]
	v_mfma_f32_16x16x32_bf16 v[20:23], v[150:153], v[206:209], v[20:23]
	v_mfma_f32_16x16x32_bf16 v[12:15], v[158:161], v[206:209], v[12:15]
	v_mfma_f32_16x16x32_bf16 v[48:51], v[162:165], v[178:181], v[48:51]
	v_mfma_f32_16x16x32_bf16 v[40:43], v[170:173], v[178:181], v[40:43]
	v_mfma_f32_16x16x32_bf16 v[32:35], v[162:165], v[186:189], v[32:35]
	v_mfma_f32_16x16x32_bf16 v[24:27], v[170:173], v[186:189], v[24:27]
	v_mfma_f32_16x16x32_bf16 v[16:19], v[162:165], v[194:197], v[16:19]
	v_mfma_f32_16x16x32_bf16 v[8:11], v[170:173], v[194:197], v[8:11]
	v_mfma_f32_16x16x32_bf16 v[4:7], v[162:165], v[202:205], v[4:7]
	v_mfma_f32_16x16x32_bf16 v[0:3], v[170:173], v[202:205], v[0:3]
	v_mfma_f32_16x16x32_bf16 v[48:51], v[166:169], v[182:185], v[48:51]
	v_mfma_f32_16x16x32_bf16 v[40:43], v[174:177], v[182:185], v[40:43]
	v_mfma_f32_16x16x32_bf16 v[32:35], v[166:169], v[190:193], v[32:35]
	v_mfma_f32_16x16x32_bf16 v[24:27], v[174:177], v[190:193], v[24:27]
	v_mfma_f32_16x16x32_bf16 v[16:19], v[166:169], v[198:201], v[16:19]
	v_mfma_f32_16x16x32_bf16 v[8:11], v[174:177], v[198:201], v[8:11]
	v_mfma_f32_16x16x32_bf16 v[4:7], v[166:169], v[206:209], v[4:7]
	v_mfma_f32_16x16x32_bf16 v[0:3], v[174:177], v[206:209], v[0:3]
	s_setprio 0
	s_barrier
	s_add_i32 s63, 0, 0x18000
	s_add_i32 s64, 0, 0x1c000
	v_add_u32_e32 v158, s63, v144
	v_add_u32_e32 v174, s64, v144
	ds_read_b128 v[146:149], v158
	ds_read_b128 v[150:153], v158 offset:1024
	ds_read_b128 v[154:157], v158 offset:2048
	ds_read_b128 v[158:161], v158 offset:3072
	ds_read_b128 v[162:165], v174
	ds_read_b128 v[166:169], v174 offset:1024
	ds_read_b128 v[170:173], v174 offset:2048
	ds_read_b128 v[174:177], v174 offset:3072
	s_add_u32 s42, s42, 0x40000
	s_addc_u32 s43, s43, 0
	s_mov_b32 m0, s53
	v_lshl_add_u64 v[218:219], s[42:43], 0, v[130:131]
	ds_read_b128 v[178:181], v145 offset:32768
	ds_read_b128 v[182:185], v145 offset:33792
	ds_read_b128 v[186:189], v145 offset:34816
	ds_read_b128 v[190:193], v145 offset:35840
	ds_read_b128 v[194:197], v145 offset:36864
	ds_read_b128 v[198:201], v145 offset:37888
	ds_read_b128 v[202:205], v145 offset:38912
	ds_read_b128 v[206:209], v145 offset:39936
	global_load_lds_dwordx4 v[218:219], off
	v_lshl_add_u64 v[218:219], s[42:43], 0, v[132:133]
	s_mov_b32 m0, s54
	s_nop 0
	global_load_lds_dwordx4 v[218:219], off
	s_waitcnt vmcnt(8)
	s_waitcnt lgkmcnt(0)
	s_barrier
	s_setprio 1
	v_mfma_f32_16x16x32_bf16 v[124:127], v[146:149], v[178:181], v[124:127]
	v_mfma_f32_16x16x32_bf16 v[120:123], v[154:157], v[178:181], v[120:123]
	v_mfma_f32_16x16x32_bf16 v[116:119], v[146:149], v[186:189], v[116:119]
	v_mfma_f32_16x16x32_bf16 v[108:111], v[154:157], v[186:189], v[108:111]
	v_mfma_f32_16x16x32_bf16 v[100:103], v[146:149], v[194:197], v[100:103]
	v_mfma_f32_16x16x32_bf16 v[92:95], v[154:157], v[194:197], v[92:95]
	v_mfma_f32_16x16x32_bf16 v[84:87], v[146:149], v[202:205], v[84:87]
	v_mfma_f32_16x16x32_bf16 v[76:79], v[154:157], v[202:205], v[76:79]
	v_mfma_f32_16x16x32_bf16 v[124:127], v[150:153], v[182:185], v[124:127]
	v_mfma_f32_16x16x32_bf16 v[120:123], v[158:161], v[182:185], v[120:123]
	v_mfma_f32_16x16x32_bf16 v[116:119], v[150:153], v[190:193], v[116:119]
	v_mfma_f32_16x16x32_bf16 v[108:111], v[158:161], v[190:193], v[108:111]
	v_mfma_f32_16x16x32_bf16 v[100:103], v[150:153], v[198:201], v[100:103]
	v_mfma_f32_16x16x32_bf16 v[92:95], v[158:161], v[198:201], v[92:95]
	v_mfma_f32_16x16x32_bf16 v[84:87], v[150:153], v[206:209], v[84:87]
	v_mfma_f32_16x16x32_bf16 v[76:79], v[158:161], v[206:209], v[76:79]
	v_mfma_f32_16x16x32_bf16 v[112:115], v[162:165], v[178:181], v[112:115]
	v_mfma_f32_16x16x32_bf16 v[104:107], v[170:173], v[178:181], v[104:107]
	v_mfma_f32_16x16x32_bf16 v[96:99], v[162:165], v[186:189], v[96:99]
	v_mfma_f32_16x16x32_bf16 v[88:91], v[170:173], v[186:189], v[88:91]
	v_mfma_f32_16x16x32_bf16 v[80:83], v[162:165], v[194:197], v[80:83]
	v_mfma_f32_16x16x32_bf16 v[72:75], v[170:173], v[194:197], v[72:75]
	v_mfma_f32_16x16x32_bf16 v[68:71], v[162:165], v[202:205], v[68:71]
	v_mfma_f32_16x16x32_bf16 v[64:67], v[170:173], v[202:205], v[64:67]
	v_mfma_f32_16x16x32_bf16 v[112:115], v[166:169], v[182:185], v[112:115]
	v_mfma_f32_16x16x32_bf16 v[104:107], v[174:177], v[182:185], v[104:107]
	v_mfma_f32_16x16x32_bf16 v[96:99], v[166:169], v[190:193], v[96:99]
	v_mfma_f32_16x16x32_bf16 v[88:91], v[174:177], v[190:193], v[88:91]
	v_mfma_f32_16x16x32_bf16 v[80:83], v[166:169], v[198:201], v[80:83]
	v_mfma_f32_16x16x32_bf16 v[72:75], v[174:177], v[198:201], v[72:75]
	v_mfma_f32_16x16x32_bf16 v[68:71], v[166:169], v[206:209], v[68:71]
	v_mfma_f32_16x16x32_bf16 v[64:67], v[174:177], v[206:209], v[64:67]
	s_setprio 0
	s_barrier
	s_add_i32 s42, s63, s46
	v_lshl_add_u64 v[210:211], v[210:211], 0, s[8:9]
	s_mov_b32 m0, s42
	ds_read_b128 v[178:181], v145 offset:49152
	ds_read_b128 v[182:185], v145 offset:50176
	ds_read_b128 v[186:189], v145 offset:51200
	ds_read_b128 v[190:193], v145 offset:52224
	ds_read_b128 v[194:197], v145 offset:53248
	ds_read_b128 v[198:201], v145 offset:54272
	ds_read_b128 v[202:205], v145 offset:55296
	ds_read_b128 v[206:209], v145 offset:56320
	global_load_lds_dwordx4 v[210:211], off
	s_add_i32 m0, s42, 0x2000
	s_add_u32 s40, s40, 0x40080
	v_lshl_add_u64 v[210:211], v[212:213], 0, s[8:9]
	s_addc_u32 s41, s41, 0
	s_add_i32 s42, s64, s46
	global_load_lds_dwordx4 v[210:211], off
	v_lshl_add_u64 v[210:211], s[40:41], 0, v[128:129]
	s_mov_b32 m0, s42
	s_nop 0
	global_load_lds_dwordx4 v[210:211], off
	v_lshl_add_u64 v[210:211], s[40:41], 0, v[134:135]
	s_add_i32 m0, s42, 0x2000
	s_nop 0
	global_load_lds_dwordx4 v[210:211], off
	v_lshl_add_u64 v[210:211], v[214:215], 0, s[8:9]
	s_mov_b32 m0, s56
	s_nop 0
	global_load_lds_dwordx4 v[210:211], off
	v_lshl_add_u64 v[210:211], v[216:217], 0, s[8:9]
	s_mov_b32 m0, s57
	s_nop 0
	global_load_lds_dwordx4 v[210:211], off
	s_waitcnt vmcnt(8)
	s_waitcnt lgkmcnt(0)
	s_barrier
	s_setprio 1
	v_mfma_f32_16x16x32_bf16 v[60:63], v[146:149], v[178:181], v[60:63]
	v_mfma_f32_16x16x32_bf16 v[56:59], v[154:157], v[178:181], v[56:59]
	v_mfma_f32_16x16x32_bf16 v[52:55], v[146:149], v[186:189], v[52:55]
	v_mfma_f32_16x16x32_bf16 v[44:47], v[154:157], v[186:189], v[44:47]
	v_mfma_f32_16x16x32_bf16 v[36:39], v[146:149], v[194:197], v[36:39]
	v_mfma_f32_16x16x32_bf16 v[28:31], v[154:157], v[194:197], v[28:31]
	v_mfma_f32_16x16x32_bf16 v[20:23], v[146:149], v[202:205], v[20:23]
	v_mfma_f32_16x16x32_bf16 v[12:15], v[154:157], v[202:205], v[12:15]
	v_mfma_f32_16x16x32_bf16 v[60:63], v[150:153], v[182:185], v[60:63]
	v_mfma_f32_16x16x32_bf16 v[56:59], v[158:161], v[182:185], v[56:59]
	v_mfma_f32_16x16x32_bf16 v[52:55], v[150:153], v[190:193], v[52:55]
	v_mfma_f32_16x16x32_bf16 v[44:47], v[158:161], v[190:193], v[44:47]
	v_mfma_f32_16x16x32_bf16 v[36:39], v[150:153], v[198:201], v[36:39]
	v_mfma_f32_16x16x32_bf16 v[28:31], v[158:161], v[198:201], v[28:31]
	v_mfma_f32_16x16x32_bf16 v[20:23], v[150:153], v[206:209], v[20:23]
	v_mfma_f32_16x16x32_bf16 v[12:15], v[158:161], v[206:209], v[12:15]
	v_mfma_f32_16x16x32_bf16 v[48:51], v[162:165], v[178:181], v[48:51]
	v_mfma_f32_16x16x32_bf16 v[40:43], v[170:173], v[178:181], v[40:43]
	v_mfma_f32_16x16x32_bf16 v[32:35], v[162:165], v[186:189], v[32:35]
	v_mfma_f32_16x16x32_bf16 v[24:27], v[170:173], v[186:189], v[24:27]
	v_mfma_f32_16x16x32_bf16 v[16:19], v[162:165], v[194:197], v[16:19]
	v_mfma_f32_16x16x32_bf16 v[8:11], v[170:173], v[194:197], v[8:11]
	v_mfma_f32_16x16x32_bf16 v[4:7], v[162:165], v[202:205], v[4:7]
	v_mfma_f32_16x16x32_bf16 v[0:3], v[170:173], v[202:205], v[0:3]
	v_mfma_f32_16x16x32_bf16 v[48:51], v[166:169], v[182:185], v[48:51]
	v_mfma_f32_16x16x32_bf16 v[40:43], v[174:177], v[182:185], v[40:43]
	v_mfma_f32_16x16x32_bf16 v[32:35], v[166:169], v[190:193], v[32:35]
	v_mfma_f32_16x16x32_bf16 v[24:27], v[174:177], v[190:193], v[24:27]
	v_mfma_f32_16x16x32_bf16 v[16:19], v[166:169], v[198:201], v[16:19]
	v_mfma_f32_16x16x32_bf16 v[8:11], v[174:177], v[198:201], v[8:11]
	v_mfma_f32_16x16x32_bf16 v[4:7], v[166:169], v[206:209], v[4:7]
	v_mfma_f32_16x16x32_bf16 v[0:3], v[174:177], v[206:209], v[0:3]
	s_setprio 0
	s_barrier
	s_add_i32 s62, s62, 2
	s_add_u32 s34, s34, 0x100
	s_addc_u32 s35, s35, 0
	s_cmp_gt_u32 s62, 13
	s_cbranch_scc0 .LBB0_654
	s_cmpk_lt_u32 s45, 0x100
	s_cbranch_scc0 .LBB0_627
	s_barrier
	s_branch .LBB0_627

.LBB0_721:
	s_lshl_b32 s7, s7, 5
	s_add_i32 s13, 0, 0x18000
	s_lshl_b32 s5, s8, 6
	s_lshl_b32 s12, s8, 13
	s_and_b32 s16, s7, 0x60
	s_add_i32 s17, s13, s6
	s_mov_b64 s[8:9], 0x80
	s_lshl_b32 s7, s16, 7
	v_lshl_add_u64 v[30:31], v[16:17], 0, s[8:9]
	s_mov_b32 m0, s17
	s_add_i32 s19, s17, 0x2000
	s_add_i32 s18, s27, 0x8000
	s_add_i32 s22, s27, 0xa000
	s_waitcnt vmcnt(2)
	s_barrier
	global_load_lds_dwordx4 v[30:31], off
	v_lshl_add_u64 v[36:37], v[18:19], 0, s[8:9]
	s_mov_b32 m0, s19
	v_lshl_add_u64 v[28:29], v[10:11], 0, s[8:9]
	v_lshl_add_u64 v[38:39], v[12:13], 0, s[8:9]
	s_add_u32 s8, s2, 0x40080
	global_load_lds_dwordx4 v[36:37], off
	s_mov_b32 m0, s18
	s_addc_u32 s9, s3, 0
	s_add_i32 s29, 0, 0x1c000
	global_load_lds_dwordx4 v[28:29], off
	s_mov_b32 m0, s22
	s_add_i32 s25, s29, s6
	global_load_lds_dwordx4 v[38:39], off
	v_lshl_add_u64 v[52:53], s[8:9], 0, v[22:23]
	s_mov_b32 m0, s25
	s_add_i32 s26, s25, 0x2000
	global_load_lds_dwordx4 v[52:53], off
	v_lshl_add_u64 v[54:55], s[8:9], 0, v[20:21]
	s_mov_b32 m0, s26
	v_lshrrev_b32_e32 v24, 1, v150
	global_load_lds_dwordx4 v[54:55], off
	v_and_b32_e32 v129, 24, v24
	v_and_b32_e32 v128, 15, v150
	v_lshlrev_b32_e32 v24, 1, v129
	v_lshlrev_b32_e32 v25, 2, v150
	v_lshl_or_b32 v24, v128, 6, v24
	v_and_b32_e32 v25, 32, v25
	v_bitop3_b32 v26, v24, s12, v25 bitop3:0xde
	v_bitop3_b32 v24, v24, s7, v25 bitop3:0xde
	s_add_i32 s30, 0, 0x10000
	s_add_i32 s33, 0, 0x14000
	v_add_u32_e32 v232, s30, v24
	s_add_u32 s36, s10, 0x40080
	s_waitcnt vmcnt(6)
	s_barrier
	v_add_u32_e32 v233, s33, v24
	v_add_u32_e32 v246, 0, v26
	v_add_u32_e32 v234, s13, v24
	v_add_u32_e32 v235, s29, v24
	s_addc_u32 s37, s11, 0
	s_add_i32 s30, s30, s6
	ds_read_b128 v[24:27], v232
	ds_read_b128 v[32:35], v232 offset:1024
	ds_read_b128 v[40:43], v232 offset:2048
	ds_read_b128 v[44:47], v232 offset:3072
	ds_read_b128 v[48:51], v233
	ds_read_b128 v[56:59], v233 offset:1024
	ds_read_b128 v[60:63], v233 offset:2048
	ds_read_b128 v[64:67], v233 offset:3072
	s_add_i32 s35, s27, 0xc000
	s_add_i32 s34, s27, 0xe000
	s_add_i32 s29, s30, 0x2000
	s_add_u32 s12, s2, 0x40100
	s_addc_u32 s13, s3, 0
	s_add_i32 s33, s33, s6
	s_add_i32 s31, s33, 0x2000
	s_add_u32 s8, s10, 0x40100
	s_addc_u32 s9, s11, 0
	s_add_u32 s6, s2, 0x40180
	s_addc_u32 s7, s3, 0
	s_add_u32 s2, s10, 0x40180
	s_addc_u32 s3, s11, 0
	s_cmpk_gt_u32 s0, 0xff
	s_mov_b32 m0, s35
	v_lshl_add_u64 v[100:101], s[36:37], 0, v[6:7]
	ds_read_b128 v[68:71], v246
	ds_read_b128 v[72:75], v246 offset:1024
	ds_read_b128 v[76:79], v246 offset:2048
	ds_read_b128 v[80:83], v246 offset:3072
	ds_read_b128 v[84:87], v246 offset:4096
	ds_read_b128 v[88:91], v246 offset:5120
	ds_read_b128 v[92:95], v246 offset:6144
	ds_read_b128 v[96:99], v246 offset:7168
	global_load_lds_dwordx4 v[100:101], off
	v_lshl_add_u64 v[100:101], s[36:37], 0, v[4:5]
	s_mov_b32 m0, s34
	s_nop 0
	global_load_lds_dwordx4 v[100:101], off
	s_waitcnt vmcnt(8)
	s_waitcnt lgkmcnt(0)
	s_barrier
	s_setprio 1
	v_mfma_f32_16x16x32_bf16 v[100:103], v[24:27], v[68:71], 0
	v_mfma_f32_16x16x32_bf16 v[104:107], v[40:43], v[68:71], 0
	v_mfma_f32_16x16x32_bf16 v[108:111], v[24:27], v[76:79], 0
	v_mfma_f32_16x16x32_bf16 v[112:115], v[40:43], v[76:79], 0
	v_mfma_f32_16x16x32_bf16 v[116:119], v[24:27], v[84:87], 0
	v_mfma_f32_16x16x32_bf16 v[120:123], v[40:43], v[84:87], 0
	v_mfma_f32_16x16x32_bf16 v[124:127], v[24:27], v[92:95], 0
	v_mfma_f32_16x16x32_bf16 v[100:103], v[32:35], v[72:75], v[100:103]
	v_mfma_f32_16x16x32_bf16 v[104:107], v[44:47], v[72:75], v[104:107]
	v_mfma_f32_16x16x32_bf16 v[108:111], v[32:35], v[80:83], v[108:111]
	v_mfma_f32_16x16x32_bf16 v[112:115], v[44:47], v[80:83], v[112:115]
	v_mfma_f32_16x16x32_bf16 v[116:119], v[32:35], v[88:91], v[116:119]
	v_mfma_f32_16x16x32_bf16 v[120:123], v[44:47], v[88:91], v[120:123]
	v_mfma_f32_16x16x32_bf16 v[124:127], v[32:35], v[96:99], v[124:127]
	v_mfma_f32_16x16x32_bf16 v[130:133], v[40:43], v[92:95], 0
	v_mfma_f32_16x16x32_bf16 v[130:133], v[44:47], v[96:99], v[130:133]
	v_mfma_f32_16x16x32_bf16 v[134:137], v[48:51], v[68:71], 0
	v_mfma_f32_16x16x32_bf16 v[68:71], v[60:63], v[68:71], 0
	v_mfma_f32_16x16x32_bf16 v[134:137], v[56:59], v[72:75], v[134:137]
	v_mfma_f32_16x16x32_bf16 v[68:71], v[64:67], v[72:75], v[68:71]
	v_mfma_f32_16x16x32_bf16 v[72:75], v[48:51], v[76:79], 0
	v_mfma_f32_16x16x32_bf16 v[76:79], v[60:63], v[76:79], 0
	v_mfma_f32_16x16x32_bf16 v[72:75], v[56:59], v[80:83], v[72:75]
	v_mfma_f32_16x16x32_bf16 v[76:79], v[64:67], v[80:83], v[76:79]
	v_mfma_f32_16x16x32_bf16 v[80:83], v[48:51], v[84:87], 0
	v_mfma_f32_16x16x32_bf16 v[84:87], v[60:63], v[84:87], 0
	v_mfma_f32_16x16x32_bf16 v[80:83], v[56:59], v[88:91], v[80:83]
	v_mfma_f32_16x16x32_bf16 v[84:87], v[64:67], v[88:91], v[84:87]
	v_mfma_f32_16x16x32_bf16 v[88:91], v[48:51], v[92:95], 0
	v_mfma_f32_16x16x32_bf16 v[92:95], v[60:63], v[92:95], 0
	v_mfma_f32_16x16x32_bf16 v[88:91], v[56:59], v[96:99], v[88:91]
	v_mfma_f32_16x16x32_bf16 v[92:95], v[64:67], v[96:99], v[92:95]
	s_setprio 0
	s_barrier
	s_mov_b64 s[10:11], 0x100
	s_mov_b32 m0, s30
	v_lshl_add_u64 v[166:167], v[16:17], 0, s[10:11]
	ds_read_b128 v[96:99], v246 offset:16384
	ds_read_b128 v[138:141], v246 offset:17408
	ds_read_b128 v[142:145], v246 offset:18432
	ds_read_b128 v[146:149], v246 offset:19456
	ds_read_b128 v[150:153], v246 offset:20480
	ds_read_b128 v[154:157], v246 offset:21504
	ds_read_b128 v[158:161], v246 offset:22528
	ds_read_b128 v[162:165], v246 offset:23552
	global_load_lds_dwordx4 v[166:167], off
	v_lshl_add_u64 v[166:167], v[18:19], 0, s[10:11]
	s_mov_b32 m0, s29
	s_nop 0
	global_load_lds_dwordx4 v[166:167], off
	v_lshl_add_u64 v[166:167], s[12:13], 0, v[22:23]
	s_mov_b32 m0, s33
	s_nop 0
	global_load_lds_dwordx4 v[166:167], off
	v_lshl_add_u64 v[166:167], s[12:13], 0, v[20:21]
	s_mov_b32 m0, s31
	s_nop 0
	global_load_lds_dwordx4 v[166:167], off
	v_lshl_add_u64 v[166:167], v[10:11], 0, s[10:11]
	s_mov_b32 m0, s27
	s_nop 0
	global_load_lds_dwordx4 v[166:167], off
	v_lshl_add_u64 v[166:167], v[12:13], 0, s[10:11]
	s_mov_b32 m0, s28
	s_nop 0
	global_load_lds_dwordx4 v[166:167], off
	s_waitcnt vmcnt(8)
	s_waitcnt lgkmcnt(0)
	s_barrier
	s_setprio 1
	v_mfma_f32_16x16x32_bf16 v[166:169], v[24:27], v[96:99], 0
	v_mfma_f32_16x16x32_bf16 v[174:177], v[24:27], v[142:145], 0
	v_mfma_f32_16x16x32_bf16 v[182:185], v[24:27], v[150:153], 0
	v_mfma_f32_16x16x32_bf16 v[24:27], v[24:27], v[158:161], 0
	v_mfma_f32_16x16x32_bf16 v[166:169], v[32:35], v[138:141], v[166:169]
	v_mfma_f32_16x16x32_bf16 v[174:177], v[32:35], v[146:149], v[174:177]
	v_mfma_f32_16x16x32_bf16 v[182:185], v[32:35], v[154:157], v[182:185]
	v_mfma_f32_16x16x32_bf16 v[24:27], v[32:35], v[162:165], v[24:27]
	v_mfma_f32_16x16x32_bf16 v[32:35], v[40:43], v[158:161], 0
	v_mfma_f32_16x16x32_bf16 v[170:173], v[40:43], v[96:99], 0
	v_mfma_f32_16x16x32_bf16 v[178:181], v[40:43], v[142:145], 0
	v_mfma_f32_16x16x32_bf16 v[186:189], v[40:43], v[150:153], 0
	v_mfma_f32_16x16x32_bf16 v[32:35], v[44:47], v[162:165], v[32:35]
	v_mfma_f32_16x16x32_bf16 v[170:173], v[44:47], v[138:141], v[170:173]
	v_mfma_f32_16x16x32_bf16 v[178:181], v[44:47], v[146:149], v[178:181]
	v_mfma_f32_16x16x32_bf16 v[186:189], v[44:47], v[154:157], v[186:189]
	v_mfma_f32_16x16x32_bf16 v[40:43], v[48:51], v[96:99], 0
	v_mfma_f32_16x16x32_bf16 v[44:47], v[60:63], v[96:99], 0
	v_mfma_f32_16x16x32_bf16 v[40:43], v[56:59], v[138:141], v[40:43]
	v_mfma_f32_16x16x32_bf16 v[44:47], v[64:67], v[138:141], v[44:47]
	v_mfma_f32_16x16x32_bf16 v[96:99], v[48:51], v[142:145], 0
	v_mfma_f32_16x16x32_bf16 v[138:141], v[60:63], v[142:145], 0
	v_mfma_f32_16x16x32_bf16 v[142:145], v[48:51], v[150:153], 0
	v_mfma_f32_16x16x32_bf16 v[48:51], v[48:51], v[158:161], 0
	v_mfma_f32_16x16x32_bf16 v[96:99], v[56:59], v[146:149], v[96:99]
	v_mfma_f32_16x16x32_bf16 v[142:145], v[56:59], v[154:157], v[142:145]
	v_mfma_f32_16x16x32_bf16 v[48:51], v[56:59], v[162:165], v[48:51]
	v_mfma_f32_16x16x32_bf16 v[56:59], v[60:63], v[158:161], 0
	v_mfma_f32_16x16x32_bf16 v[138:141], v[64:67], v[146:149], v[138:141]
	v_mfma_f32_16x16x32_bf16 v[146:149], v[60:63], v[150:153], 0
	v_mfma_f32_16x16x32_bf16 v[56:59], v[64:67], v[162:165], v[56:59]
	v_mfma_f32_16x16x32_bf16 v[146:149], v[64:67], v[154:157], v[146:149]
	s_setprio 0
	s_barrier
	ds_read_b128 v[60:63], v234
	ds_read_b128 v[64:67], v234 offset:1024
	ds_read_b128 v[150:153], v234 offset:2048
	ds_read_b128 v[154:157], v234 offset:3072
	ds_read_b128 v[158:161], v235
	ds_read_b128 v[162:165], v235 offset:1024
	ds_read_b128 v[190:193], v235 offset:2048
	ds_read_b128 v[194:197], v235 offset:3072
	s_mov_b32 m0, s23
	v_lshl_add_u64 v[230:231], s[8:9], 0, v[6:7]
	ds_read_b128 v[198:201], v246 offset:32768
	ds_read_b128 v[202:205], v246 offset:33792
	ds_read_b128 v[206:209], v246 offset:34816
	ds_read_b128 v[210:213], v246 offset:35840
	ds_read_b128 v[214:217], v246 offset:36864
	ds_read_b128 v[218:221], v246 offset:37888
	ds_read_b128 v[222:225], v246 offset:38912
	ds_read_b128 v[226:229], v246 offset:39936
	global_load_lds_dwordx4 v[230:231], off
	v_lshl_add_u64 v[230:231], s[8:9], 0, v[4:5]
	s_mov_b32 m0, s24
	s_nop 0
	global_load_lds_dwordx4 v[230:231], off
	s_waitcnt vmcnt(8)
	s_waitcnt lgkmcnt(0)
	s_barrier
	s_setprio 1
	v_mfma_f32_16x16x32_bf16 v[100:103], v[60:63], v[198:201], v[100:103]
	v_mfma_f32_16x16x32_bf16 v[104:107], v[150:153], v[198:201], v[104:107]
	v_mfma_f32_16x16x32_bf16 v[108:111], v[60:63], v[206:209], v[108:111]
	v_mfma_f32_16x16x32_bf16 v[112:115], v[150:153], v[206:209], v[112:115]
	v_mfma_f32_16x16x32_bf16 v[116:119], v[60:63], v[214:217], v[116:119]
	v_mfma_f32_16x16x32_bf16 v[120:123], v[150:153], v[214:217], v[120:123]
	v_mfma_f32_16x16x32_bf16 v[124:127], v[60:63], v[222:225], v[124:127]
	v_mfma_f32_16x16x32_bf16 v[100:103], v[64:67], v[202:205], v[100:103]
	v_mfma_f32_16x16x32_bf16 v[104:107], v[154:157], v[202:205], v[104:107]
	v_mfma_f32_16x16x32_bf16 v[108:111], v[64:67], v[210:213], v[108:111]
	v_mfma_f32_16x16x32_bf16 v[112:115], v[154:157], v[210:213], v[112:115]
	v_mfma_f32_16x16x32_bf16 v[116:119], v[64:67], v[218:221], v[116:119]
	v_mfma_f32_16x16x32_bf16 v[120:123], v[154:157], v[218:221], v[120:123]
	v_mfma_f32_16x16x32_bf16 v[124:127], v[64:67], v[226:229], v[124:127]
	v_mfma_f32_16x16x32_bf16 v[130:133], v[150:153], v[222:225], v[130:133]
	v_mfma_f32_16x16x32_bf16 v[130:133], v[154:157], v[226:229], v[130:133]
	v_mfma_f32_16x16x32_bf16 v[68:71], v[190:193], v[198:201], v[68:71]
	v_mfma_f32_16x16x32_bf16 v[72:75], v[158:161], v[206:209], v[72:75]
	v_mfma_f32_16x16x32_bf16 v[76:79], v[190:193], v[206:209], v[76:79]
	v_mfma_f32_16x16x32_bf16 v[80:83], v[158:161], v[214:217], v[80:83]
	v_mfma_f32_16x16x32_bf16 v[84:87], v[190:193], v[214:217], v[84:87]
	v_mfma_f32_16x16x32_bf16 v[88:91], v[158:161], v[222:225], v[88:91]
	v_mfma_f32_16x16x32_bf16 v[92:95], v[190:193], v[222:225], v[92:95]
	v_mfma_f32_16x16x32_bf16 v[134:137], v[158:161], v[198:201], v[134:137]
	v_mfma_f32_16x16x32_bf16 v[68:71], v[194:197], v[202:205], v[68:71]
	v_mfma_f32_16x16x32_bf16 v[72:75], v[162:165], v[210:213], v[72:75]
	v_mfma_f32_16x16x32_bf16 v[76:79], v[194:197], v[210:213], v[76:79]
	v_mfma_f32_16x16x32_bf16 v[80:83], v[162:165], v[218:221], v[80:83]
	v_mfma_f32_16x16x32_bf16 v[84:87], v[194:197], v[218:221], v[84:87]
	v_mfma_f32_16x16x32_bf16 v[88:91], v[162:165], v[226:229], v[88:91]
	v_mfma_f32_16x16x32_bf16 v[92:95], v[194:197], v[226:229], v[92:95]
	v_mfma_f32_16x16x32_bf16 v[134:137], v[162:165], v[202:205], v[134:137]
	s_setprio 0
	s_barrier
	s_mov_b64 s[8:9], 0x180
	s_mov_b32 m0, s17
	v_lshl_add_u64 v[230:231], v[16:17], 0, s[8:9]
	ds_read_b128 v[198:201], v246 offset:49152
	ds_read_b128 v[202:205], v246 offset:50176
	ds_read_b128 v[206:209], v246 offset:51200
	ds_read_b128 v[210:213], v246 offset:52224
	ds_read_b128 v[214:217], v246 offset:53248
	ds_read_b128 v[218:221], v246 offset:54272
	ds_read_b128 v[222:225], v246 offset:55296
	ds_read_b128 v[226:229], v246 offset:56320
	global_load_lds_dwordx4 v[230:231], off
	v_lshl_add_u64 v[230:231], v[18:19], 0, s[8:9]
	s_mov_b32 m0, s19
	v_lshl_add_u64 v[22:23], s[6:7], 0, v[22:23]
	global_load_lds_dwordx4 v[230:231], off
	s_mov_b32 m0, s25
	v_lshl_add_u64 v[20:21], s[6:7], 0, v[20:21]
	global_load_lds_dwordx4 v[22:23], off
	s_mov_b32 m0, s26
	s_nop 0
	global_load_lds_dwordx4 v[20:21], off
	v_lshl_add_u64 v[20:21], v[10:11], 0, s[8:9]
	s_mov_b32 m0, s18
	s_nop 0
	global_load_lds_dwordx4 v[20:21], off
	v_lshl_add_u64 v[20:21], v[12:13], 0, s[8:9]
	s_mov_b32 m0, s22
	s_nop 0
	global_load_lds_dwordx4 v[20:21], off
	s_waitcnt vmcnt(8)
	s_waitcnt lgkmcnt(0)
	s_barrier
	s_setprio 1
	v_mfma_f32_16x16x32_bf16 v[20:23], v[60:63], v[198:201], v[166:169]
	v_mfma_f32_16x16x32_bf16 v[24:27], v[60:63], v[222:225], v[24:27]
	v_mfma_f32_16x16x32_bf16 v[32:35], v[150:153], v[222:225], v[32:35]
	v_mfma_f32_16x16x32_bf16 v[20:23], v[64:67], v[202:205], v[20:23]
	v_mfma_f32_16x16x32_bf16 v[166:169], v[150:153], v[198:201], v[170:173]
	v_mfma_f32_16x16x32_bf16 v[170:173], v[60:63], v[206:209], v[174:177]
	v_mfma_f32_16x16x32_bf16 v[174:177], v[150:153], v[206:209], v[178:181]
	v_mfma_f32_16x16x32_bf16 v[178:181], v[60:63], v[214:217], v[182:185]
	v_mfma_f32_16x16x32_bf16 v[182:185], v[150:153], v[214:217], v[186:189]
	v_mfma_f32_16x16x32_bf16 v[24:27], v[64:67], v[226:229], v[24:27]
	v_mfma_f32_16x16x32_bf16 v[32:35], v[154:157], v[226:229], v[32:35]
	v_mfma_f32_16x16x32_bf16 v[166:169], v[154:157], v[202:205], v[166:169]
	v_mfma_f32_16x16x32_bf16 v[170:173], v[64:67], v[210:213], v[170:173]
	v_mfma_f32_16x16x32_bf16 v[174:177], v[154:157], v[210:213], v[174:177]
	v_mfma_f32_16x16x32_bf16 v[178:181], v[64:67], v[218:221], v[178:181]
	v_mfma_f32_16x16x32_bf16 v[182:185], v[154:157], v[218:221], v[182:185]
	v_mfma_f32_16x16x32_bf16 v[40:43], v[158:161], v[198:201], v[40:43]
	v_mfma_f32_16x16x32_bf16 v[44:47], v[190:193], v[198:201], v[44:47]
	v_mfma_f32_16x16x32_bf16 v[60:63], v[158:161], v[206:209], v[96:99]
	v_mfma_f32_16x16x32_bf16 v[64:67], v[190:193], v[206:209], v[138:141]
	v_mfma_f32_16x16x32_bf16 v[96:99], v[158:161], v[214:217], v[142:145]
	v_mfma_f32_16x16x32_bf16 v[48:51], v[158:161], v[222:225], v[48:51]
	v_mfma_f32_16x16x32_bf16 v[56:59], v[190:193], v[222:225], v[56:59]
	v_mfma_f32_16x16x32_bf16 v[40:43], v[162:165], v[202:205], v[40:43]
	v_mfma_f32_16x16x32_bf16 v[44:47], v[194:197], v[202:205], v[44:47]
	v_mfma_f32_16x16x32_bf16 v[60:63], v[162:165], v[210:213], v[60:63]
	v_mfma_f32_16x16x32_bf16 v[64:67], v[194:197], v[210:213], v[64:67]
	v_mfma_f32_16x16x32_bf16 v[96:99], v[162:165], v[218:221], v[96:99]
	v_mfma_f32_16x16x32_bf16 v[138:141], v[190:193], v[214:217], v[146:149]
	v_mfma_f32_16x16x32_bf16 v[48:51], v[162:165], v[226:229], v[48:51]
	v_mfma_f32_16x16x32_bf16 v[56:59], v[194:197], v[226:229], v[56:59]
	v_mfma_f32_16x16x32_bf16 v[138:141], v[194:197], v[218:221], v[138:141]
	s_setprio 0
	s_barrier
	ds_read_b128 v[142:145], v232
	ds_read_b128 v[146:149], v232 offset:1024
	ds_read_b128 v[150:153], v232 offset:2048
	ds_read_b128 v[154:157], v232 offset:3072
	ds_read_b128 v[158:161], v233
	ds_read_b128 v[162:165], v233 offset:1024
	ds_read_b128 v[186:189], v233 offset:2048
	ds_read_b128 v[190:193], v233 offset:3072
	s_mov_b32 m0, s35
	v_lshl_add_u64 v[6:7], s[2:3], 0, v[6:7]
	ds_read_b128 v[194:197], v246
	ds_read_b128 v[198:201], v246 offset:1024
	ds_read_b128 v[202:205], v246 offset:2048
	ds_read_b128 v[206:209], v246 offset:3072
	ds_read_b128 v[210:213], v246 offset:4096
	ds_read_b128 v[214:217], v246 offset:5120
	ds_read_b128 v[218:221], v246 offset:6144
	ds_read_b128 v[222:225], v246 offset:7168
	global_load_lds_dwordx4 v[6:7], off
	v_lshl_add_u64 v[4:5], s[2:3], 0, v[4:5]
	s_mov_b32 m0, s34
	s_nop 0
	global_load_lds_dwordx4 v[4:5], off
	s_waitcnt vmcnt(8)
	s_waitcnt lgkmcnt(0)
	s_barrier
	s_setprio 1
	v_mfma_f32_16x16x32_bf16 v[4:7], v[142:145], v[194:197], v[100:103]
	v_mfma_f32_16x16x32_bf16 v[100:103], v[150:153], v[194:197], v[104:107]
	v_mfma_f32_16x16x32_bf16 v[104:107], v[142:145], v[202:205], v[108:111]
	v_mfma_f32_16x16x32_bf16 v[108:111], v[150:153], v[202:205], v[112:115]
	v_mfma_f32_16x16x32_bf16 v[112:115], v[142:145], v[210:213], v[116:119]
	v_mfma_f32_16x16x32_bf16 v[116:119], v[150:153], v[210:213], v[120:123]
	v_mfma_f32_16x16x32_bf16 v[120:123], v[142:145], v[218:221], v[124:127]
	v_mfma_f32_16x16x32_bf16 v[124:127], v[150:153], v[218:221], v[130:133]
	v_mfma_f32_16x16x32_bf16 v[4:7], v[146:149], v[198:201], v[4:7]
	v_mfma_f32_16x16x32_bf16 v[100:103], v[154:157], v[198:201], v[100:103]
	v_mfma_f32_16x16x32_bf16 v[104:107], v[146:149], v[206:209], v[104:107]
	v_mfma_f32_16x16x32_bf16 v[108:111], v[154:157], v[206:209], v[108:111]
	v_mfma_f32_16x16x32_bf16 v[112:115], v[146:149], v[214:217], v[112:115]
	v_mfma_f32_16x16x32_bf16 v[116:119], v[154:157], v[214:217], v[116:119]
	v_mfma_f32_16x16x32_bf16 v[120:123], v[146:149], v[222:225], v[120:123]
	v_mfma_f32_16x16x32_bf16 v[124:127], v[154:157], v[222:225], v[124:127]
	v_mfma_f32_16x16x32_bf16 v[68:71], v[186:189], v[194:197], v[68:71]
	v_mfma_f32_16x16x32_bf16 v[72:75], v[158:161], v[202:205], v[72:75]
	v_mfma_f32_16x16x32_bf16 v[76:79], v[186:189], v[202:205], v[76:79]
	v_mfma_f32_16x16x32_bf16 v[80:83], v[158:161], v[210:213], v[80:83]
	v_mfma_f32_16x16x32_bf16 v[84:87], v[186:189], v[210:213], v[84:87]
	v_mfma_f32_16x16x32_bf16 v[88:91], v[158:161], v[218:221], v[88:91]
	v_mfma_f32_16x16x32_bf16 v[130:133], v[158:161], v[194:197], v[134:137]
	v_mfma_f32_16x16x32_bf16 v[68:71], v[190:193], v[198:201], v[68:71]
	v_mfma_f32_16x16x32_bf16 v[72:75], v[162:165], v[206:209], v[72:75]
	v_mfma_f32_16x16x32_bf16 v[76:79], v[190:193], v[206:209], v[76:79]
	v_mfma_f32_16x16x32_bf16 v[80:83], v[162:165], v[214:217], v[80:83]
	v_mfma_f32_16x16x32_bf16 v[84:87], v[190:193], v[214:217], v[84:87]
	v_mfma_f32_16x16x32_bf16 v[134:137], v[162:165], v[222:225], v[88:91]
	v_mfma_f32_16x16x32_bf16 v[88:91], v[186:189], v[218:221], v[92:95]
	v_mfma_f32_16x16x32_bf16 v[130:133], v[162:165], v[198:201], v[130:133]
	v_mfma_f32_16x16x32_bf16 v[194:197], v[190:193], v[222:225], v[88:91]
	s_setprio 0
	s_barrier
	s_mov_b32 m0, s30
	s_nop 2
	ds_read_b128 v[88:91], v246 offset:16384
	ds_read_b128 v[92:95], v246 offset:17408
	ds_read_b128 v[198:201], v246 offset:18432
	ds_read_b128 v[202:205], v246 offset:19456
	ds_read_b128 v[206:209], v246 offset:20480
	ds_read_b128 v[210:213], v246 offset:21504
	ds_read_b128 v[214:217], v246 offset:22528
	ds_read_b128 v[218:221], v246 offset:23552
	global_load_lds_dwordx4 v[16:17], off
	s_mov_b32 m0, s29
	s_nop 0
	global_load_lds_dwordx4 v[18:19], off
	s_mov_b32 m0, s33
	s_nop 0
	global_load_lds_dwordx4 v[14:15], off
	s_mov_b32 m0, s31
	s_nop 0
	global_load_lds_dwordx4 v[8:9], off
	s_mov_b32 m0, s27
	s_nop 0
	global_load_lds_dwordx4 v[10:11], off
	s_mov_b32 m0, s28
	s_nop 0
	global_load_lds_dwordx4 v[12:13], off
	s_waitcnt vmcnt(8)
	s_waitcnt lgkmcnt(0)
	s_barrier
	s_setprio 1
	v_mfma_f32_16x16x32_bf16 v[8:11], v[142:145], v[88:91], v[20:23]
	v_mfma_f32_16x16x32_bf16 v[222:225], v[146:149], v[92:95], v[8:11]
	v_mfma_f32_16x16x32_bf16 v[8:11], v[150:153], v[88:91], v[166:169]
	v_mfma_f32_16x16x32_bf16 v[166:169], v[154:157], v[92:95], v[8:11]
	v_mfma_f32_16x16x32_bf16 v[8:11], v[142:145], v[198:201], v[170:173]
	v_mfma_f32_16x16x32_bf16 v[170:173], v[146:149], v[202:205], v[8:11]
	v_mfma_f32_16x16x32_bf16 v[8:11], v[150:153], v[198:201], v[174:177]
	v_mfma_f32_16x16x32_bf16 v[174:177], v[154:157], v[202:205], v[8:11]
	v_mfma_f32_16x16x32_bf16 v[8:11], v[142:145], v[206:209], v[178:181]
	v_mfma_f32_16x16x32_bf16 v[178:181], v[146:149], v[210:213], v[8:11]
	v_mfma_f32_16x16x32_bf16 v[8:11], v[150:153], v[206:209], v[182:185]
	v_mfma_f32_16x16x32_bf16 v[182:185], v[154:157], v[210:213], v[8:11]
	v_mfma_f32_16x16x32_bf16 v[8:11], v[142:145], v[214:217], v[24:27]
	v_mfma_f32_16x16x32_bf16 v[142:145], v[146:149], v[218:221], v[8:11]
	v_mfma_f32_16x16x32_bf16 v[8:11], v[150:153], v[214:217], v[32:35]
	v_mfma_f32_16x16x32_bf16 v[146:149], v[154:157], v[218:221], v[8:11]
	v_mfma_f32_16x16x32_bf16 v[8:11], v[158:161], v[88:91], v[40:43]
	v_mfma_f32_16x16x32_bf16 v[150:153], v[162:165], v[92:95], v[8:11]
	v_mfma_f32_16x16x32_bf16 v[8:11], v[186:189], v[88:91], v[44:47]
	v_mfma_f32_16x16x32_bf16 v[154:157], v[190:193], v[92:95], v[8:11]
	v_mfma_f32_16x16x32_bf16 v[8:11], v[158:161], v[198:201], v[60:63]
	v_mfma_f32_16x16x32_bf16 v[226:229], v[162:165], v[202:205], v[8:11]
	v_mfma_f32_16x16x32_bf16 v[8:11], v[186:189], v[198:201], v[64:67]
	v_mfma_f32_16x16x32_bf16 v[198:201], v[190:193], v[202:205], v[8:11]
	v_mfma_f32_16x16x32_bf16 v[8:11], v[158:161], v[206:209], v[96:99]
	v_mfma_f32_16x16x32_bf16 v[202:205], v[162:165], v[210:213], v[8:11]
	v_mfma_f32_16x16x32_bf16 v[8:11], v[186:189], v[206:209], v[138:141]
	v_mfma_f32_16x16x32_bf16 v[138:141], v[190:193], v[210:213], v[8:11]
	v_mfma_f32_16x16x32_bf16 v[8:11], v[158:161], v[214:217], v[48:51]
	v_mfma_f32_16x16x32_bf16 v[158:161], v[162:165], v[218:221], v[8:11]
	v_mfma_f32_16x16x32_bf16 v[8:11], v[186:189], v[214:217], v[56:59]
	v_mfma_f32_16x16x32_bf16 v[162:165], v[190:193], v[218:221], v[8:11]
	s_setprio 0
	s_barrier
	ds_read_b128 v[186:189], v234
	ds_read_b128 v[190:193], v234 offset:1024
	ds_read_b128 v[206:209], v234 offset:2048
	ds_read_b128 v[210:213], v234 offset:3072
	ds_read_b128 v[214:217], v235
	ds_read_b128 v[218:221], v235 offset:1024
	ds_read_b128 v[230:233], v235 offset:2048
	ds_read_b128 v[234:237], v235 offset:3072
	s_mov_b32 m0, s23
	ds_read_b128 v[24:27], v246 offset:32768
	ds_read_b128 v[32:35], v246 offset:33792
	ds_read_b128 v[48:51], v246 offset:34816
	ds_read_b128 v[56:59], v246 offset:35840
	ds_read_b128 v[60:63], v246 offset:36864
	ds_read_b128 v[96:99], v246 offset:37888
	ds_read_b128 v[238:241], v246 offset:38912
	ds_read_b128 v[242:245], v246 offset:39936
	global_load_lds_dwordx4 v[0:1], off
	s_mov_b32 m0, s24
	s_nop 0
	global_load_lds_dwordx4 v[2:3], off
	s_waitcnt vmcnt(8)
	s_waitcnt lgkmcnt(0)
	s_barrier
	s_setprio 1
	v_mfma_f32_16x16x32_bf16 v[0:3], v[186:189], v[24:27], v[4:7]
	v_mfma_f32_16x16x32_bf16 v[40:43], v[190:193], v[32:35], v[0:3]
	v_mfma_f32_16x16x32_bf16 v[0:3], v[206:209], v[24:27], v[100:103]
	v_mfma_f32_16x16x32_bf16 v[44:47], v[210:213], v[32:35], v[0:3]
	v_mfma_f32_16x16x32_bf16 v[0:3], v[186:189], v[48:51], v[104:107]
	v_mfma_f32_16x16x32_bf16 v[16:19], v[190:193], v[56:59], v[0:3]
	v_mfma_f32_16x16x32_bf16 v[0:3], v[206:209], v[48:51], v[108:111]
	v_mfma_f32_16x16x32_bf16 v[20:23], v[210:213], v[56:59], v[0:3]
	v_mfma_f32_16x16x32_bf16 v[0:3], v[186:189], v[60:63], v[112:115]
	v_mfma_f32_16x16x32_bf16 v[8:11], v[190:193], v[96:99], v[0:3]
	v_mfma_f32_16x16x32_bf16 v[0:3], v[206:209], v[60:63], v[116:119]
	v_mfma_f32_16x16x32_bf16 v[12:15], v[210:213], v[96:99], v[0:3]
	v_mfma_f32_16x16x32_bf16 v[0:3], v[186:189], v[238:241], v[120:123]
	v_mfma_f32_16x16x32_bf16 v[4:7], v[206:209], v[238:241], v[124:127]
	v_mfma_f32_16x16x32_bf16 v[0:3], v[190:193], v[242:245], v[0:3]
	v_mfma_f32_16x16x32_bf16 v[4:7], v[210:213], v[242:245], v[4:7]
	v_mfma_f32_16x16x32_bf16 v[64:67], v[214:217], v[24:27], v[130:133]
	v_mfma_f32_16x16x32_bf16 v[24:27], v[230:233], v[24:27], v[68:71]
	v_mfma_f32_16x16x32_bf16 v[92:95], v[234:237], v[32:35], v[24:27]
	v_mfma_f32_16x16x32_bf16 v[24:27], v[214:217], v[48:51], v[72:75]
	v_mfma_f32_16x16x32_bf16 v[88:91], v[218:221], v[32:35], v[64:67]
	v_mfma_f32_16x16x32_bf16 v[64:67], v[218:221], v[56:59], v[24:27]
	v_mfma_f32_16x16x32_bf16 v[24:27], v[230:233], v[48:51], v[76:79]
	v_mfma_f32_16x16x32_bf16 v[68:71], v[234:237], v[56:59], v[24:27]
	v_mfma_f32_16x16x32_bf16 v[24:27], v[214:217], v[60:63], v[80:83]
	v_mfma_f32_16x16x32_bf16 v[48:51], v[218:221], v[96:99], v[24:27]
	v_mfma_f32_16x16x32_bf16 v[24:27], v[230:233], v[60:63], v[84:87]
	v_mfma_f32_16x16x32_bf16 v[56:59], v[234:237], v[96:99], v[24:27]
	v_mfma_f32_16x16x32_bf16 v[24:27], v[214:217], v[238:241], v[134:137]
	v_mfma_f32_16x16x32_bf16 v[32:35], v[230:233], v[238:241], v[194:197]
	v_mfma_f32_16x16x32_bf16 v[24:27], v[218:221], v[242:245], v[24:27]
	v_mfma_f32_16x16x32_bf16 v[32:35], v[234:237], v[242:245], v[32:35]
	s_setprio 0
	s_barrier
	s_mov_b32 m0, s17
	ds_read_b128 v[80:83], v246 offset:49152
	ds_read_b128 v[84:87], v246 offset:50176
	ds_read_b128 v[104:107], v246 offset:51200
	ds_read_b128 v[108:111], v246 offset:52224
	ds_read_b128 v[130:133], v246 offset:53248
	ds_read_b128 v[134:137], v246 offset:54272
	ds_read_b128 v[194:197], v246 offset:55296
	ds_read_b128 v[238:241], v246 offset:56320
	global_load_lds_dwordx4 v[30:31], off
	s_mov_b32 m0, s19
	s_nop 0
	global_load_lds_dwordx4 v[36:37], off
	s_mov_b32 m0, s25
	s_nop 0
	global_load_lds_dwordx4 v[52:53], off
	s_mov_b32 m0, s26
	s_nop 0
	global_load_lds_dwordx4 v[54:55], off
	s_mov_b32 m0, s18
	s_nop 0
	global_load_lds_dwordx4 v[28:29], off
	s_mov_b32 m0, s22
	s_nop 0
	global_load_lds_dwordx4 v[38:39], off
	s_waitcnt vmcnt(8)
	s_waitcnt lgkmcnt(0)
	s_barrier
	s_setprio 1
	v_mfma_f32_16x16x32_bf16 v[28:31], v[186:189], v[80:83], v[222:225]
	v_mfma_f32_16x16x32_bf16 v[96:99], v[190:193], v[84:87], v[28:31]
	v_mfma_f32_16x16x32_bf16 v[28:31], v[206:209], v[80:83], v[166:169]
	v_mfma_f32_16x16x32_bf16 v[100:103], v[210:213], v[84:87], v[28:31]
	v_mfma_f32_16x16x32_bf16 v[28:31], v[186:189], v[104:107], v[170:173]
	v_mfma_f32_16x16x32_bf16 v[72:75], v[190:193], v[108:111], v[28:31]
	v_mfma_f32_16x16x32_bf16 v[28:31], v[206:209], v[104:107], v[174:177]
	v_mfma_f32_16x16x32_bf16 v[76:79], v[210:213], v[108:111], v[28:31]
	v_mfma_f32_16x16x32_bf16 v[28:31], v[186:189], v[130:133], v[178:181]
	v_mfma_f32_16x16x32_bf16 v[52:55], v[190:193], v[134:137], v[28:31]
	v_mfma_f32_16x16x32_bf16 v[28:31], v[206:209], v[130:133], v[182:185]
	v_mfma_f32_16x16x32_bf16 v[60:63], v[210:213], v[134:137], v[28:31]
	v_mfma_f32_16x16x32_bf16 v[28:31], v[186:189], v[194:197], v[142:145]
	v_mfma_f32_16x16x32_bf16 v[36:39], v[206:209], v[194:197], v[146:149]
	v_mfma_f32_16x16x32_bf16 v[28:31], v[190:193], v[238:241], v[28:31]
	v_mfma_f32_16x16x32_bf16 v[36:39], v[210:213], v[238:241], v[36:39]
	v_mfma_f32_16x16x32_bf16 v[112:115], v[214:217], v[80:83], v[150:153]
	v_mfma_f32_16x16x32_bf16 v[80:83], v[230:233], v[80:83], v[154:157]
	v_mfma_f32_16x16x32_bf16 v[124:127], v[234:237], v[84:87], v[80:83]
	v_mfma_f32_16x16x32_bf16 v[80:83], v[214:217], v[104:107], v[226:229]
	v_mfma_f32_16x16x32_bf16 v[120:123], v[218:221], v[84:87], v[112:115]
	v_mfma_f32_16x16x32_bf16 v[112:115], v[218:221], v[108:111], v[80:83]
	v_mfma_f32_16x16x32_bf16 v[80:83], v[230:233], v[104:107], v[198:201]
	v_mfma_f32_16x16x32_bf16 v[116:119], v[234:237], v[108:111], v[80:83]
	v_mfma_f32_16x16x32_bf16 v[80:83], v[214:217], v[130:133], v[202:205]
	v_mfma_f32_16x16x32_bf16 v[104:107], v[218:221], v[134:137], v[80:83]
	v_mfma_f32_16x16x32_bf16 v[80:83], v[230:233], v[130:133], v[138:141]
	v_mfma_f32_16x16x32_bf16 v[108:111], v[234:237], v[134:137], v[80:83]
	v_mfma_f32_16x16x32_bf16 v[80:83], v[214:217], v[194:197], v[158:161]
	v_mfma_f32_16x16x32_bf16 v[84:87], v[230:233], v[194:197], v[162:165]
	v_mfma_f32_16x16x32_bf16 v[80:83], v[218:221], v[238:241], v[80:83]
	v_mfma_f32_16x16x32_bf16 v[84:87], v[234:237], v[238:241], v[84:87]
	s_setprio 0
	s_barrier
	s_cbranch_scc1 .LBB0_723
	s_barrier
